# GEMM k-loops: s_setprio 2 from the pre-barrier wait through the LDS-DMA issue, 0 elsewhere
# baseline (speedup 1.0000x reference)
.Lg1a_cont:
	s_lshl3_add_u32 s22, s5, s25
	s_lshl_b32 s23, s6, 1
	s_mul_i32 s0, s22, 0x40000
	s_add_u32 s14, s44, s0
	s_addc_u32 s15, s45, 0
	s_mul_i32 s0, s23, 0x40000
	s_add_u32 s16, s48, s0
	s_addc_u32 s17, s49, 0
	s_add_u32 s18, s16, 0x40000
	s_addc_u32 s19, s17, 0
	s_lshl_b32 s0, s22, 9
	s_add_u32 s30, s90, s0
	s_addc_u32 s31, s91, 0
	s_waitcnt vmcnt(0) lgkmcnt(0)
	s_barrier
	v_and_b32_e32 v166, 63, v148
	v_lshlrev_b32_e32 v166, 4, v166
	s_mov_b32 m0, 0xc400
	s_mov_b64 exec, 0xffffffff
	global_load_lds_dwordx4 v166, s[30:31]
	s_mov_b64 exec, -1
	s_add_u32 m0, s20, 0x0
	s_nop 0
	global_load_lds_dwordx4 v160, s[14:15]
	global_load_lds_dwordx4 v160, s[14:15] offset:1024
	s_add_u32 s14, s14, 0x2000
	s_addc_u32 s15, s15, 0
	s_add_u32 m0, s20, 0x2000
	s_nop 0
	global_load_lds_dwordx4 v160, s[16:17]
	global_load_lds_dwordx4 v160, s[16:17] offset:1024
	s_add_u32 s16, s16, 0x2000
	s_addc_u32 s17, s17, 0
	s_add_u32 m0, s20, 0x4000
	s_nop 0
	global_load_lds_dwordx4 v160, s[18:19]
	global_load_lds_dwordx4 v160, s[18:19] offset:1024
	s_add_u32 s18, s18, 0x2000
	s_addc_u32 s19, s19, 0
	s_waitcnt vmcnt(0)
	s_barrier
	s_add_u32 m0, s20, 0x6000
	s_nop 0
	global_load_lds_dwordx4 v160, s[14:15]
	global_load_lds_dwordx4 v160, s[14:15] offset:1024
	s_add_u32 s14, s14, 0x2000
	s_addc_u32 s15, s15, 0
	s_add_u32 m0, s20, 0x8000
	s_nop 0
	global_load_lds_dwordx4 v160, s[16:17]
	global_load_lds_dwordx4 v160, s[16:17] offset:1024
	s_add_u32 s16, s16, 0x2000
	s_addc_u32 s17, s17, 0
	s_add_u32 m0, s20, 0xa400
	s_nop 0
	global_load_lds_dwordx4 v160, s[18:19]
	global_load_lds_dwordx4 v160, s[18:19] offset:1024
	s_add_u32 s18, s18, 0x2000
	s_addc_u32 s19, s19, 0
	ds_read_b128 v[64:67], v154 offset:0
	ds_read_b128 v[72:75], v156 offset:8192
	ds_read_b128 v[76:79], v156 offset:10240
	ds_read_b128 v[80:83], v156 offset:16384
	ds_read_b128 v[150:153], v156 offset:18432
	ds_read_b128 v[68:71], v154 offset:2048
	s_waitcnt lgkmcnt(4)
	v_mfma_f32_32x32x16_bf16 v[48:63], v[64:67], v[72:75], 0
	s_waitcnt lgkmcnt(3)
	v_mfma_f32_32x32x16_bf16 v[32:47], v[64:67], v[76:79], 0
	s_waitcnt lgkmcnt(2)
	v_mfma_f32_32x32x16_bf16 v[132:147], v[64:67], v[80:83], 0
	s_waitcnt lgkmcnt(1)
	v_mfma_f32_32x32x16_bf16 v[116:131], v[64:67], v[150:153], 0
	ds_read_b128 v[64:67], v155 offset:0
	s_waitcnt lgkmcnt(1)
	v_mfma_f32_32x32x16_bf16 v[84:99], v[68:71], v[150:153], 0
	ds_read_b128 v[150:153], v157 offset:18432
	v_mfma_f32_32x32x16_bf16 v[100:115], v[68:71], v[80:83], 0
	ds_read_b128 v[80:83], v157 offset:16384
	v_mfma_f32_32x32x16_bf16 v[0:15], v[68:71], v[76:79], 0
	ds_read_b128 v[76:79], v157 offset:10240
	v_mfma_f32_32x32x16_bf16 v[16:31], v[68:71], v[72:75], 0
	ds_read_b128 v[72:75], v157 offset:8192
	ds_read_b128 v[68:71], v155 offset:2048
	s_waitcnt lgkmcnt(4)
	v_mfma_f32_32x32x16_bf16 v[116:131], v[64:67], v[150:153], v[116:131]
	s_waitcnt lgkmcnt(3)
	v_mfma_f32_32x32x16_bf16 v[132:147], v[64:67], v[80:83], v[132:147]
	s_waitcnt lgkmcnt(2)
	v_mfma_f32_32x32x16_bf16 v[32:47], v[64:67], v[76:79], v[32:47]
	s_waitcnt lgkmcnt(1)
	v_mfma_f32_32x32x16_bf16 v[48:63], v[64:67], v[72:75], v[48:63]
	s_setprio 2
	s_waitcnt vmcnt(0) lgkmcnt(0)
	s_barrier
	ds_read_b128 v[64:67], v154 offset:24576
	s_add_u32 m0, s20, 0x0
	s_nop 0
	global_load_lds_dwordx4 v160, s[14:15]
	global_load_lds_dwordx4 v160, s[14:15] offset:1024
	s_add_u32 s14, s14, 0x2000
	s_addc_u32 s15, s15, 0
	v_mfma_f32_32x32x16_bf16 v[16:31], v[68:71], v[72:75], v[16:31]
	ds_read_b128 v[72:75], v156 offset:32768
	s_add_u32 m0, s20, 0x2000
	s_nop 0
	global_load_lds_dwordx4 v160, s[16:17]
	global_load_lds_dwordx4 v160, s[16:17] offset:1024
	s_add_u32 s16, s16, 0x2000
	s_addc_u32 s17, s17, 0
	v_mfma_f32_32x32x16_bf16 v[0:15], v[68:71], v[76:79], v[0:15]
	ds_read_b128 v[76:79], v156 offset:34816
	s_add_u32 m0, s20, 0x4000
	s_nop 0
	global_load_lds_dwordx4 v160, s[18:19]
	global_load_lds_dwordx4 v160, s[18:19] offset:1024
	s_add_u32 s18, s18, 0x2000
	s_addc_u32 s19, s19, 0
	s_setprio 0
	v_mfma_f32_32x32x16_bf16 v[100:115], v[68:71], v[80:83], v[100:115]
	ds_read_b128 v[80:83], v156 offset:41984
	v_mfma_f32_32x32x16_bf16 v[84:99], v[68:71], v[150:153], v[84:99]
	ds_read_b128 v[150:153], v156 offset:44032
	ds_read_b128 v[68:71], v154 offset:26624
	s_waitcnt lgkmcnt(4)
	v_mfma_f32_32x32x16_bf16 v[48:63], v[64:67], v[72:75], v[48:63]
	s_waitcnt lgkmcnt(3)
	v_mfma_f32_32x32x16_bf16 v[32:47], v[64:67], v[76:79], v[32:47]
	s_waitcnt lgkmcnt(2)
	v_mfma_f32_32x32x16_bf16 v[132:147], v[64:67], v[80:83], v[132:147]
	s_waitcnt lgkmcnt(1)
	v_mfma_f32_32x32x16_bf16 v[116:131], v[64:67], v[150:153], v[116:131]
	ds_read_b128 v[64:67], v155 offset:24576
	s_waitcnt lgkmcnt(1)
	v_mfma_f32_32x32x16_bf16 v[84:99], v[68:71], v[150:153], v[84:99]
	ds_read_b128 v[150:153], v157 offset:44032
	v_mfma_f32_32x32x16_bf16 v[100:115], v[68:71], v[80:83], v[100:115]
	ds_read_b128 v[80:83], v157 offset:41984
	v_mfma_f32_32x32x16_bf16 v[0:15], v[68:71], v[76:79], v[0:15]
	ds_read_b128 v[76:79], v157 offset:34816
	v_mfma_f32_32x32x16_bf16 v[16:31], v[68:71], v[72:75], v[16:31]
	ds_read_b128 v[72:75], v157 offset:32768
	ds_read_b128 v[68:71], v155 offset:26624
	s_waitcnt lgkmcnt(4)
	v_mfma_f32_32x32x16_bf16 v[116:131], v[64:67], v[150:153], v[116:131]
	s_waitcnt lgkmcnt(3)
	v_mfma_f32_32x32x16_bf16 v[132:147], v[64:67], v[80:83], v[132:147]
	s_waitcnt lgkmcnt(2)
	v_mfma_f32_32x32x16_bf16 v[32:47], v[64:67], v[76:79], v[32:47]
	s_waitcnt lgkmcnt(1)
	v_mfma_f32_32x32x16_bf16 v[48:63], v[64:67], v[72:75], v[48:63]
	s_setprio 2
	s_waitcnt vmcnt(0) lgkmcnt(0)
	s_barrier
	ds_read_b128 v[64:67], v154 offset:0
	s_add_u32 m0, s20, 0x6000
	s_nop 0
	global_load_lds_dwordx4 v160, s[14:15]
	global_load_lds_dwordx4 v160, s[14:15] offset:1024
	s_add_u32 s14, s14, 0x2000
	s_addc_u32 s15, s15, 0
	v_mfma_f32_32x32x16_bf16 v[16:31], v[68:71], v[72:75], v[16:31]
	ds_read_b128 v[72:75], v156 offset:8192
	s_add_u32 m0, s20, 0x8000
	s_nop 0
	global_load_lds_dwordx4 v160, s[16:17]
	global_load_lds_dwordx4 v160, s[16:17] offset:1024
	s_add_u32 s16, s16, 0x2000
	s_addc_u32 s17, s17, 0
	v_mfma_f32_32x32x16_bf16 v[0:15], v[68:71], v[76:79], v[0:15]
	ds_read_b128 v[76:79], v156 offset:10240
	s_add_u32 m0, s20, 0xa400
	s_nop 0
	global_load_lds_dwordx4 v160, s[18:19]
	global_load_lds_dwordx4 v160, s[18:19] offset:1024
	s_add_u32 s18, s18, 0x2000
	s_addc_u32 s19, s19, 0
	s_setprio 0
	v_mfma_f32_32x32x16_bf16 v[100:115], v[68:71], v[80:83], v[100:115]
	ds_read_b128 v[80:83], v156 offset:16384
	v_mfma_f32_32x32x16_bf16 v[84:99], v[68:71], v[150:153], v[84:99]
	ds_read_b128 v[150:153], v156 offset:18432
	ds_read_b128 v[68:71], v154 offset:2048
	s_mov_b32 s21, 14
.Lg1a_kloop:
	s_waitcnt lgkmcnt(4)
	v_mfma_f32_32x32x16_bf16 v[48:63], v[64:67], v[72:75], v[48:63]
	s_waitcnt lgkmcnt(3)
	v_mfma_f32_32x32x16_bf16 v[32:47], v[64:67], v[76:79], v[32:47]
	s_waitcnt lgkmcnt(2)
	v_mfma_f32_32x32x16_bf16 v[132:147], v[64:67], v[80:83], v[132:147]
	s_waitcnt lgkmcnt(1)
	v_mfma_f32_32x32x16_bf16 v[116:131], v[64:67], v[150:153], v[116:131]
	ds_read_b128 v[64:67], v155 offset:0
	s_waitcnt lgkmcnt(1)
	v_mfma_f32_32x32x16_bf16 v[84:99], v[68:71], v[150:153], v[84:99]
	ds_read_b128 v[150:153], v157 offset:18432
	v_mfma_f32_32x32x16_bf16 v[100:115], v[68:71], v[80:83], v[100:115]
	ds_read_b128 v[80:83], v157 offset:16384
	v_mfma_f32_32x32x16_bf16 v[0:15], v[68:71], v[76:79], v[0:15]
	ds_read_b128 v[76:79], v157 offset:10240
	v_mfma_f32_32x32x16_bf16 v[16:31], v[68:71], v[72:75], v[16:31]
	ds_read_b128 v[72:75], v157 offset:8192
	ds_read_b128 v[68:71], v155 offset:2048
	s_waitcnt lgkmcnt(4)
	v_mfma_f32_32x32x16_bf16 v[116:131], v[64:67], v[150:153], v[116:131]
	s_waitcnt lgkmcnt(3)
	v_mfma_f32_32x32x16_bf16 v[132:147], v[64:67], v[80:83], v[132:147]
	s_waitcnt lgkmcnt(2)
	v_mfma_f32_32x32x16_bf16 v[32:47], v[64:67], v[76:79], v[32:47]
	s_waitcnt lgkmcnt(1)
	v_mfma_f32_32x32x16_bf16 v[48:63], v[64:67], v[72:75], v[48:63]
	s_setprio 2
	s_waitcnt vmcnt(0) lgkmcnt(0)
	s_barrier
	ds_read_b128 v[64:67], v154 offset:24576
	s_add_u32 m0, s20, 0x0
	s_nop 0
	global_load_lds_dwordx4 v160, s[14:15]
	global_load_lds_dwordx4 v160, s[14:15] offset:1024
	s_add_u32 s14, s14, 0x2000
	s_addc_u32 s15, s15, 0
	v_mfma_f32_32x32x16_bf16 v[16:31], v[68:71], v[72:75], v[16:31]
	ds_read_b128 v[72:75], v156 offset:32768
	s_add_u32 m0, s20, 0x2000
	s_nop 0
	global_load_lds_dwordx4 v160, s[16:17]
	global_load_lds_dwordx4 v160, s[16:17] offset:1024
	s_add_u32 s16, s16, 0x2000
	s_addc_u32 s17, s17, 0
	v_mfma_f32_32x32x16_bf16 v[0:15], v[68:71], v[76:79], v[0:15]
	ds_read_b128 v[76:79], v156 offset:34816
	s_add_u32 m0, s20, 0x4000
	s_nop 0
	global_load_lds_dwordx4 v160, s[18:19]
	global_load_lds_dwordx4 v160, s[18:19] offset:1024
	s_add_u32 s18, s18, 0x2000
	s_addc_u32 s19, s19, 0
	s_setprio 0
	v_mfma_f32_32x32x16_bf16 v[100:115], v[68:71], v[80:83], v[100:115]
	ds_read_b128 v[80:83], v156 offset:41984
	v_mfma_f32_32x32x16_bf16 v[84:99], v[68:71], v[150:153], v[84:99]
	ds_read_b128 v[150:153], v156 offset:44032
	ds_read_b128 v[68:71], v154 offset:26624
	s_waitcnt lgkmcnt(4)
	v_mfma_f32_32x32x16_bf16 v[48:63], v[64:67], v[72:75], v[48:63]
	s_waitcnt lgkmcnt(3)
	v_mfma_f32_32x32x16_bf16 v[32:47], v[64:67], v[76:79], v[32:47]
	s_waitcnt lgkmcnt(2)
	v_mfma_f32_32x32x16_bf16 v[132:147], v[64:67], v[80:83], v[132:147]
	s_waitcnt lgkmcnt(1)
	v_mfma_f32_32x32x16_bf16 v[116:131], v[64:67], v[150:153], v[116:131]
	ds_read_b128 v[64:67], v155 offset:24576
	s_waitcnt lgkmcnt(1)
	v_mfma_f32_32x32x16_bf16 v[84:99], v[68:71], v[150:153], v[84:99]
	ds_read_b128 v[150:153], v157 offset:44032
	v_mfma_f32_32x32x16_bf16 v[100:115], v[68:71], v[80:83], v[100:115]
	ds_read_b128 v[80:83], v157 offset:41984
	v_mfma_f32_32x32x16_bf16 v[0:15], v[68:71], v[76:79], v[0:15]
	ds_read_b128 v[76:79], v157 offset:34816
	v_mfma_f32_32x32x16_bf16 v[16:31], v[68:71], v[72:75], v[16:31]
	ds_read_b128 v[72:75], v157 offset:32768
	ds_read_b128 v[68:71], v155 offset:26624
	s_waitcnt lgkmcnt(4)
	v_mfma_f32_32x32x16_bf16 v[116:131], v[64:67], v[150:153], v[116:131]
	s_waitcnt lgkmcnt(3)
	v_mfma_f32_32x32x16_bf16 v[132:147], v[64:67], v[80:83], v[132:147]
	s_waitcnt lgkmcnt(2)
	v_mfma_f32_32x32x16_bf16 v[32:47], v[64:67], v[76:79], v[32:47]
	s_waitcnt lgkmcnt(1)
	v_mfma_f32_32x32x16_bf16 v[48:63], v[64:67], v[72:75], v[48:63]
	s_setprio 2
	s_waitcnt vmcnt(0) lgkmcnt(0)
	s_barrier
	ds_read_b128 v[64:67], v154 offset:0
	s_add_u32 m0, s20, 0x6000
	s_nop 0
	global_load_lds_dwordx4 v160, s[14:15]
	global_load_lds_dwordx4 v160, s[14:15] offset:1024
	s_add_u32 s14, s14, 0x2000
	s_addc_u32 s15, s15, 0
	v_mfma_f32_32x32x16_bf16 v[16:31], v[68:71], v[72:75], v[16:31]
	ds_read_b128 v[72:75], v156 offset:8192
	s_add_u32 m0, s20, 0x8000
	s_nop 0
	global_load_lds_dwordx4 v160, s[16:17]
	global_load_lds_dwordx4 v160, s[16:17] offset:1024
	s_add_u32 s16, s16, 0x2000
	s_addc_u32 s17, s17, 0
	v_mfma_f32_32x32x16_bf16 v[0:15], v[68:71], v[76:79], v[0:15]
	ds_read_b128 v[76:79], v156 offset:10240
	s_add_u32 m0, s20, 0xa400
	s_nop 0
	global_load_lds_dwordx4 v160, s[18:19]
	global_load_lds_dwordx4 v160, s[18:19] offset:1024
	s_add_u32 s18, s18, 0x2000
	s_addc_u32 s19, s19, 0
	s_setprio 0
	v_mfma_f32_32x32x16_bf16 v[100:115], v[68:71], v[80:83], v[100:115]
	ds_read_b128 v[80:83], v156 offset:16384
	v_mfma_f32_32x32x16_bf16 v[84:99], v[68:71], v[150:153], v[84:99]
	ds_read_b128 v[150:153], v156 offset:18432
	ds_read_b128 v[68:71], v154 offset:2048
	s_sub_u32 s21, s21, 1
	s_cmp_lg_u32 s21, 0
	s_cbranch_scc1 .Lg1a_kloop
	s_waitcnt lgkmcnt(4)
	v_mfma_f32_32x32x16_bf16 v[48:63], v[64:67], v[72:75], v[48:63]
	s_waitcnt lgkmcnt(3)
	v_mfma_f32_32x32x16_bf16 v[32:47], v[64:67], v[76:79], v[32:47]
	s_waitcnt lgkmcnt(2)
	v_mfma_f32_32x32x16_bf16 v[132:147], v[64:67], v[80:83], v[132:147]
	s_waitcnt lgkmcnt(1)
	v_mfma_f32_32x32x16_bf16 v[116:131], v[64:67], v[150:153], v[116:131]
	ds_read_b128 v[64:67], v155 offset:0
	s_waitcnt lgkmcnt(1)
	v_mfma_f32_32x32x16_bf16 v[84:99], v[68:71], v[150:153], v[84:99]
	ds_read_b128 v[150:153], v157 offset:18432
	v_mfma_f32_32x32x16_bf16 v[100:115], v[68:71], v[80:83], v[100:115]
	ds_read_b128 v[80:83], v157 offset:16384
	v_mfma_f32_32x32x16_bf16 v[0:15], v[68:71], v[76:79], v[0:15]
	ds_read_b128 v[76:79], v157 offset:10240
	v_mfma_f32_32x32x16_bf16 v[16:31], v[68:71], v[72:75], v[16:31]
	ds_read_b128 v[72:75], v157 offset:8192
	ds_read_b128 v[68:71], v155 offset:2048
	s_waitcnt lgkmcnt(4)
	v_mfma_f32_32x32x16_bf16 v[116:131], v[64:67], v[150:153], v[116:131]
	s_waitcnt lgkmcnt(3)
	v_mfma_f32_32x32x16_bf16 v[132:147], v[64:67], v[80:83], v[132:147]
	s_waitcnt lgkmcnt(2)
	v_mfma_f32_32x32x16_bf16 v[32:47], v[64:67], v[76:79], v[32:47]
	s_waitcnt lgkmcnt(1)
	v_mfma_f32_32x32x16_bf16 v[48:63], v[64:67], v[72:75], v[48:63]
	s_waitcnt vmcnt(0) lgkmcnt(0)
	s_barrier
	ds_read_b128 v[64:67], v154 offset:24576
	v_mfma_f32_32x32x16_bf16 v[16:31], v[68:71], v[72:75], v[16:31]
	ds_read_b128 v[72:75], v156 offset:32768
	v_mfma_f32_32x32x16_bf16 v[0:15], v[68:71], v[76:79], v[0:15]
	ds_read_b128 v[76:79], v156 offset:34816
	v_mfma_f32_32x32x16_bf16 v[100:115], v[68:71], v[80:83], v[100:115]
	ds_read_b128 v[80:83], v156 offset:41984
	v_mfma_f32_32x32x16_bf16 v[84:99], v[68:71], v[150:153], v[84:99]
	ds_read_b128 v[150:153], v156 offset:44032
	ds_read_b128 v[68:71], v154 offset:26624
	s_waitcnt lgkmcnt(4)
	v_mfma_f32_32x32x16_bf16 v[48:63], v[64:67], v[72:75], v[48:63]
	s_waitcnt lgkmcnt(3)
	v_mfma_f32_32x32x16_bf16 v[32:47], v[64:67], v[76:79], v[32:47]
	s_waitcnt lgkmcnt(2)
	v_mfma_f32_32x32x16_bf16 v[132:147], v[64:67], v[80:83], v[132:147]
	s_waitcnt lgkmcnt(1)
	v_mfma_f32_32x32x16_bf16 v[116:131], v[64:67], v[150:153], v[116:131]
	ds_read_b128 v[64:67], v155 offset:24576
	s_waitcnt lgkmcnt(1)
	v_mfma_f32_32x32x16_bf16 v[84:99], v[68:71], v[150:153], v[84:99]
	ds_read_b128 v[150:153], v157 offset:44032
	v_mfma_f32_32x32x16_bf16 v[100:115], v[68:71], v[80:83], v[100:115]
	ds_read_b128 v[80:83], v157 offset:41984
	v_mfma_f32_32x32x16_bf16 v[0:15], v[68:71], v[76:79], v[0:15]
	ds_read_b128 v[76:79], v157 offset:34816
	v_mfma_f32_32x32x16_bf16 v[16:31], v[68:71], v[72:75], v[16:31]
	ds_read_b128 v[72:75], v157 offset:32768
	ds_read_b128 v[68:71], v155 offset:26624
	s_waitcnt lgkmcnt(4)
	v_mfma_f32_32x32x16_bf16 v[116:131], v[64:67], v[150:153], v[116:131]
	s_waitcnt lgkmcnt(3)
	v_mfma_f32_32x32x16_bf16 v[132:147], v[64:67], v[80:83], v[132:147]
	s_waitcnt lgkmcnt(2)
	v_mfma_f32_32x32x16_bf16 v[32:47], v[64:67], v[76:79], v[32:47]
	s_waitcnt lgkmcnt(1)
	v_mfma_f32_32x32x16_bf16 v[48:63], v[64:67], v[72:75], v[48:63]
	s_waitcnt lgkmcnt(0)
	v_mfma_f32_32x32x16_bf16 v[16:31], v[68:71], v[72:75], v[16:31]
	v_mfma_f32_32x32x16_bf16 v[0:15], v[68:71], v[76:79], v[0:15]
	v_mfma_f32_32x32x16_bf16 v[100:115], v[68:71], v[80:83], v[100:115]
	v_mfma_f32_32x32x16_bf16 v[84:99], v[68:71], v[150:153], v[84:99]
	s_nop 7
	s_nop 7
	s_mov_b32 s24, 0
	s_mov_b32 s4, s22
	s_mov_b32 s0, s23

.Lg2a_cont:
	s_lshl3_add_u32 s30, s7, s33
	s_lshl_b32 s31, s11, 1
	s_mul_i32 s2, s30, 0x150000
	s_add_u32 s22, s46, s2
	s_addc_u32 s23, s47, 0
	s_mul_i32 s2, s31, 0x60000
	s_add_u32 s2, s2, 0xa80000
	s_add_u32 s24, s48, s2
	s_addc_u32 s25, s49, 0
	s_add_u32 s26, s24, 0x60000
	s_addc_u32 s27, s25, 0
	s_waitcnt vmcnt(0) lgkmcnt(0)
	s_barrier
	s_add_u32 m0, s28, 0x0
	s_nop 0
	global_load_lds_dwordx4 v166, s[22:23]
	s_add_u32 m0, s28, 0x400
	s_nop 0
	global_load_lds_dwordx4 v167, s[22:23]
	s_add_u32 s22, s22, 64
	s_addc_u32 s23, s23, 0
	s_add_u32 m0, s28, 0x2000
	s_nop 0
	global_load_lds_dwordx4 v165, s[24:25]
	global_load_lds_dwordx4 v165, s[24:25] offset:1024
	s_add_u32 s24, s24, 0x2000
	s_addc_u32 s25, s25, 0
	s_add_u32 m0, s28, 0x4000
	s_nop 0
	global_load_lds_dwordx4 v165, s[26:27]
	global_load_lds_dwordx4 v165, s[26:27] offset:1024
	s_add_u32 s26, s26, 0x2000
	s_addc_u32 s27, s27, 0
	s_waitcnt vmcnt(0)
	s_barrier
	s_add_u32 m0, s28, 0x6000
	s_nop 0
	global_load_lds_dwordx4 v166, s[22:23]
	s_add_u32 m0, s28, 0x6400
	s_nop 0
	global_load_lds_dwordx4 v167, s[22:23]
	s_add_u32 s22, s22, 64
	s_addc_u32 s23, s23, 0
	s_add_u32 m0, s28, 0x8000
	s_nop 0
	global_load_lds_dwordx4 v165, s[24:25]
	global_load_lds_dwordx4 v165, s[24:25] offset:1024
	s_add_u32 s24, s24, 0x2000
	s_addc_u32 s25, s25, 0
	s_add_u32 m0, s28, 0xa400
	s_nop 0
	global_load_lds_dwordx4 v165, s[26:27]
	global_load_lds_dwordx4 v165, s[26:27] offset:1024
	s_add_u32 s26, s26, 0x2000
	s_addc_u32 s27, s27, 0
	ds_read_b128 v[64:67], v151 offset:0
	ds_read_b128 v[72:75], v157 offset:8192
	ds_read_b128 v[126:129], v157 offset:10240
	ds_read_b128 v[152:155], v157 offset:16384
	ds_read_b128 v[160:163], v157 offset:18432
	ds_read_b128 v[68:71], v151 offset:2048
	s_waitcnt lgkmcnt(4)
	v_mfma_f32_32x32x16_bf16 v[48:63], v[64:67], v[72:75], 0
	s_waitcnt lgkmcnt(3)
	v_mfma_f32_32x32x16_bf16 v[32:47], v[64:67], v[126:129], 0
	s_waitcnt lgkmcnt(2)
	v_mfma_f32_32x32x16_bf16 v[78:93], v[64:67], v[152:155], 0
	s_waitcnt lgkmcnt(1)
	v_mfma_f32_32x32x16_bf16 v[94:109], v[64:67], v[160:163], 0
	ds_read_b128 v[64:67], v156 offset:0
	s_waitcnt lgkmcnt(1)
	v_mfma_f32_32x32x16_bf16 v[132:147], v[68:71], v[160:163], 0
	ds_read_b128 v[160:163], v164 offset:18432
	v_mfma_f32_32x32x16_bf16 v[110:125], v[68:71], v[152:155], 0
	ds_read_b128 v[152:155], v164 offset:16384
	v_mfma_f32_32x32x16_bf16 v[0:15], v[68:71], v[126:129], 0
	ds_read_b128 v[126:129], v164 offset:10240
	v_mfma_f32_32x32x16_bf16 v[16:31], v[68:71], v[72:75], 0
	ds_read_b128 v[72:75], v164 offset:8192
	ds_read_b128 v[68:71], v156 offset:2048
	s_waitcnt lgkmcnt(4)
	v_mfma_f32_32x32x16_bf16 v[94:109], v[64:67], v[160:163], v[94:109]
	s_waitcnt lgkmcnt(3)
	v_mfma_f32_32x32x16_bf16 v[78:93], v[64:67], v[152:155], v[78:93]
	s_waitcnt lgkmcnt(2)
	v_mfma_f32_32x32x16_bf16 v[32:47], v[64:67], v[126:129], v[32:47]
	s_waitcnt lgkmcnt(1)
	v_mfma_f32_32x32x16_bf16 v[48:63], v[64:67], v[72:75], v[48:63]
	s_setprio 2
	s_waitcnt vmcnt(0) lgkmcnt(0)
	s_barrier
	ds_read_b128 v[64:67], v151 offset:24576
	s_add_u32 m0, s28, 0x0
	s_nop 0
	global_load_lds_dwordx4 v166, s[22:23]
	s_add_u32 m0, s28, 0x400
	s_nop 0
	global_load_lds_dwordx4 v167, s[22:23]
	s_add_u32 s22, s22, 64
	s_addc_u32 s23, s23, 0
	v_mfma_f32_32x32x16_bf16 v[16:31], v[68:71], v[72:75], v[16:31]
	ds_read_b128 v[72:75], v157 offset:32768
	s_add_u32 m0, s28, 0x2000
	s_nop 0
	global_load_lds_dwordx4 v165, s[24:25]
	global_load_lds_dwordx4 v165, s[24:25] offset:1024
	s_add_u32 s24, s24, 0x2000
	s_addc_u32 s25, s25, 0
	v_mfma_f32_32x32x16_bf16 v[0:15], v[68:71], v[126:129], v[0:15]
	ds_read_b128 v[126:129], v157 offset:34816
	s_add_u32 m0, s28, 0x4000
	s_nop 0
	global_load_lds_dwordx4 v165, s[26:27]
	global_load_lds_dwordx4 v165, s[26:27] offset:1024
	s_add_u32 s26, s26, 0x2000
	s_addc_u32 s27, s27, 0
	s_setprio 0
	v_mfma_f32_32x32x16_bf16 v[110:125], v[68:71], v[152:155], v[110:125]
	ds_read_b128 v[152:155], v157 offset:41984
	v_mfma_f32_32x32x16_bf16 v[132:147], v[68:71], v[160:163], v[132:147]
	ds_read_b128 v[160:163], v157 offset:44032
	ds_read_b128 v[68:71], v151 offset:26624
	s_waitcnt lgkmcnt(4)
	v_mfma_f32_32x32x16_bf16 v[48:63], v[64:67], v[72:75], v[48:63]
	s_waitcnt lgkmcnt(3)
	v_mfma_f32_32x32x16_bf16 v[32:47], v[64:67], v[126:129], v[32:47]
	s_waitcnt lgkmcnt(2)
	v_mfma_f32_32x32x16_bf16 v[78:93], v[64:67], v[152:155], v[78:93]
	s_waitcnt lgkmcnt(1)
	v_mfma_f32_32x32x16_bf16 v[94:109], v[64:67], v[160:163], v[94:109]
	ds_read_b128 v[64:67], v156 offset:24576
	s_waitcnt lgkmcnt(1)
	v_mfma_f32_32x32x16_bf16 v[132:147], v[68:71], v[160:163], v[132:147]
	ds_read_b128 v[160:163], v164 offset:44032
	v_mfma_f32_32x32x16_bf16 v[110:125], v[68:71], v[152:155], v[110:125]
	ds_read_b128 v[152:155], v164 offset:41984
	v_mfma_f32_32x32x16_bf16 v[0:15], v[68:71], v[126:129], v[0:15]
	ds_read_b128 v[126:129], v164 offset:34816
	v_mfma_f32_32x32x16_bf16 v[16:31], v[68:71], v[72:75], v[16:31]
	ds_read_b128 v[72:75], v164 offset:32768
	ds_read_b128 v[68:71], v156 offset:26624
	s_waitcnt lgkmcnt(4)
	v_mfma_f32_32x32x16_bf16 v[94:109], v[64:67], v[160:163], v[94:109]
	s_waitcnt lgkmcnt(3)
	v_mfma_f32_32x32x16_bf16 v[78:93], v[64:67], v[152:155], v[78:93]
	s_waitcnt lgkmcnt(2)
	v_mfma_f32_32x32x16_bf16 v[32:47], v[64:67], v[126:129], v[32:47]
	s_waitcnt lgkmcnt(1)
	v_mfma_f32_32x32x16_bf16 v[48:63], v[64:67], v[72:75], v[48:63]
	s_setprio 2
	s_waitcnt vmcnt(0) lgkmcnt(0)
	s_barrier
	ds_read_b128 v[64:67], v151 offset:0
	s_add_u32 m0, s28, 0x6000
	s_nop 0
	global_load_lds_dwordx4 v166, s[22:23]
	s_add_u32 m0, s28, 0x6400
	s_nop 0
	global_load_lds_dwordx4 v167, s[22:23]
	s_add_u32 s22, s22, 64
	s_addc_u32 s23, s23, 0
	v_mfma_f32_32x32x16_bf16 v[16:31], v[68:71], v[72:75], v[16:31]
	ds_read_b128 v[72:75], v157 offset:8192
	s_add_u32 m0, s28, 0x8000
	s_nop 0
	global_load_lds_dwordx4 v165, s[24:25]
	global_load_lds_dwordx4 v165, s[24:25] offset:1024
	s_add_u32 s24, s24, 0x2000
	s_addc_u32 s25, s25, 0
	v_mfma_f32_32x32x16_bf16 v[0:15], v[68:71], v[126:129], v[0:15]
	ds_read_b128 v[126:129], v157 offset:10240
	s_add_u32 m0, s28, 0xa400
	s_nop 0
	global_load_lds_dwordx4 v165, s[26:27]
	global_load_lds_dwordx4 v165, s[26:27] offset:1024
	s_add_u32 s26, s26, 0x2000
	s_addc_u32 s27, s27, 0
	s_setprio 0
	v_mfma_f32_32x32x16_bf16 v[110:125], v[68:71], v[152:155], v[110:125]
	ds_read_b128 v[152:155], v157 offset:16384
	v_mfma_f32_32x32x16_bf16 v[132:147], v[68:71], v[160:163], v[132:147]
	ds_read_b128 v[160:163], v157 offset:18432
	ds_read_b128 v[68:71], v151 offset:2048
	s_mov_b32 s29, 22
.Lg2a_kloop:
	s_waitcnt lgkmcnt(4)
	v_mfma_f32_32x32x16_bf16 v[48:63], v[64:67], v[72:75], v[48:63]
	s_waitcnt lgkmcnt(3)
	v_mfma_f32_32x32x16_bf16 v[32:47], v[64:67], v[126:129], v[32:47]
	s_waitcnt lgkmcnt(2)
	v_mfma_f32_32x32x16_bf16 v[78:93], v[64:67], v[152:155], v[78:93]
	s_waitcnt lgkmcnt(1)
	v_mfma_f32_32x32x16_bf16 v[94:109], v[64:67], v[160:163], v[94:109]
	ds_read_b128 v[64:67], v156 offset:0
	s_waitcnt lgkmcnt(1)
	v_mfma_f32_32x32x16_bf16 v[132:147], v[68:71], v[160:163], v[132:147]
	ds_read_b128 v[160:163], v164 offset:18432
	v_mfma_f32_32x32x16_bf16 v[110:125], v[68:71], v[152:155], v[110:125]
	ds_read_b128 v[152:155], v164 offset:16384
	v_mfma_f32_32x32x16_bf16 v[0:15], v[68:71], v[126:129], v[0:15]
	ds_read_b128 v[126:129], v164 offset:10240
	v_mfma_f32_32x32x16_bf16 v[16:31], v[68:71], v[72:75], v[16:31]
	ds_read_b128 v[72:75], v164 offset:8192
	ds_read_b128 v[68:71], v156 offset:2048
	s_waitcnt lgkmcnt(4)
	v_mfma_f32_32x32x16_bf16 v[94:109], v[64:67], v[160:163], v[94:109]
	s_waitcnt lgkmcnt(3)
	v_mfma_f32_32x32x16_bf16 v[78:93], v[64:67], v[152:155], v[78:93]
	s_waitcnt lgkmcnt(2)
	v_mfma_f32_32x32x16_bf16 v[32:47], v[64:67], v[126:129], v[32:47]
	s_waitcnt lgkmcnt(1)
	v_mfma_f32_32x32x16_bf16 v[48:63], v[64:67], v[72:75], v[48:63]
	s_setprio 2
	s_waitcnt vmcnt(0) lgkmcnt(0)
	s_barrier
	ds_read_b128 v[64:67], v151 offset:24576
	s_add_u32 m0, s28, 0x0
	s_nop 0
	global_load_lds_dwordx4 v166, s[22:23]
	s_add_u32 m0, s28, 0x400
	s_nop 0
	global_load_lds_dwordx4 v167, s[22:23]
	s_add_u32 s22, s22, 64
	s_addc_u32 s23, s23, 0
	v_mfma_f32_32x32x16_bf16 v[16:31], v[68:71], v[72:75], v[16:31]
	ds_read_b128 v[72:75], v157 offset:32768
	s_add_u32 m0, s28, 0x2000
	s_nop 0
	global_load_lds_dwordx4 v165, s[24:25]
	global_load_lds_dwordx4 v165, s[24:25] offset:1024
	s_add_u32 s24, s24, 0x2000
	s_addc_u32 s25, s25, 0
	v_mfma_f32_32x32x16_bf16 v[0:15], v[68:71], v[126:129], v[0:15]
	ds_read_b128 v[126:129], v157 offset:34816
	s_add_u32 m0, s28, 0x4000
	s_nop 0
	global_load_lds_dwordx4 v165, s[26:27]
	global_load_lds_dwordx4 v165, s[26:27] offset:1024
	s_add_u32 s26, s26, 0x2000
	s_addc_u32 s27, s27, 0
	s_setprio 0
	v_mfma_f32_32x32x16_bf16 v[110:125], v[68:71], v[152:155], v[110:125]
	ds_read_b128 v[152:155], v157 offset:41984
	v_mfma_f32_32x32x16_bf16 v[132:147], v[68:71], v[160:163], v[132:147]
	ds_read_b128 v[160:163], v157 offset:44032
	ds_read_b128 v[68:71], v151 offset:26624
	s_waitcnt lgkmcnt(4)
	v_mfma_f32_32x32x16_bf16 v[48:63], v[64:67], v[72:75], v[48:63]
	s_waitcnt lgkmcnt(3)
	v_mfma_f32_32x32x16_bf16 v[32:47], v[64:67], v[126:129], v[32:47]
	s_waitcnt lgkmcnt(2)
	v_mfma_f32_32x32x16_bf16 v[78:93], v[64:67], v[152:155], v[78:93]
	s_waitcnt lgkmcnt(1)
	v_mfma_f32_32x32x16_bf16 v[94:109], v[64:67], v[160:163], v[94:109]
	ds_read_b128 v[64:67], v156 offset:24576
	s_waitcnt lgkmcnt(1)
	v_mfma_f32_32x32x16_bf16 v[132:147], v[68:71], v[160:163], v[132:147]
	ds_read_b128 v[160:163], v164 offset:44032
	v_mfma_f32_32x32x16_bf16 v[110:125], v[68:71], v[152:155], v[110:125]
	ds_read_b128 v[152:155], v164 offset:41984
	v_mfma_f32_32x32x16_bf16 v[0:15], v[68:71], v[126:129], v[0:15]
	ds_read_b128 v[126:129], v164 offset:34816
	v_mfma_f32_32x32x16_bf16 v[16:31], v[68:71], v[72:75], v[16:31]
	ds_read_b128 v[72:75], v164 offset:32768
	ds_read_b128 v[68:71], v156 offset:26624
	s_waitcnt lgkmcnt(4)
	v_mfma_f32_32x32x16_bf16 v[94:109], v[64:67], v[160:163], v[94:109]
	s_waitcnt lgkmcnt(3)
	v_mfma_f32_32x32x16_bf16 v[78:93], v[64:67], v[152:155], v[78:93]
	s_waitcnt lgkmcnt(2)
	v_mfma_f32_32x32x16_bf16 v[32:47], v[64:67], v[126:129], v[32:47]
	s_waitcnt lgkmcnt(1)
	v_mfma_f32_32x32x16_bf16 v[48:63], v[64:67], v[72:75], v[48:63]
	s_setprio 2
	s_waitcnt vmcnt(0) lgkmcnt(0)
	s_barrier
	ds_read_b128 v[64:67], v151 offset:0
	s_add_u32 m0, s28, 0x6000
	s_nop 0
	global_load_lds_dwordx4 v166, s[22:23]
	s_add_u32 m0, s28, 0x6400
	s_nop 0
	global_load_lds_dwordx4 v167, s[22:23]
	s_add_u32 s22, s22, 64
	s_addc_u32 s23, s23, 0
	v_mfma_f32_32x32x16_bf16 v[16:31], v[68:71], v[72:75], v[16:31]
	ds_read_b128 v[72:75], v157 offset:8192
	s_add_u32 m0, s28, 0x8000
	s_nop 0
	global_load_lds_dwordx4 v165, s[24:25]
	global_load_lds_dwordx4 v165, s[24:25] offset:1024
	s_add_u32 s24, s24, 0x2000
	s_addc_u32 s25, s25, 0
	v_mfma_f32_32x32x16_bf16 v[0:15], v[68:71], v[126:129], v[0:15]
	ds_read_b128 v[126:129], v157 offset:10240
	s_add_u32 m0, s28, 0xa400
	s_nop 0
	global_load_lds_dwordx4 v165, s[26:27]
	global_load_lds_dwordx4 v165, s[26:27] offset:1024
	s_add_u32 s26, s26, 0x2000
	s_addc_u32 s27, s27, 0
	s_setprio 0
	v_mfma_f32_32x32x16_bf16 v[110:125], v[68:71], v[152:155], v[110:125]
	ds_read_b128 v[152:155], v157 offset:16384
	v_mfma_f32_32x32x16_bf16 v[132:147], v[68:71], v[160:163], v[132:147]
	ds_read_b128 v[160:163], v157 offset:18432
	ds_read_b128 v[68:71], v151 offset:2048
	s_sub_u32 s29, s29, 1
	s_cmp_lg_u32 s29, 0
	s_cbranch_scc1 .Lg2a_kloop
	s_waitcnt lgkmcnt(4)
	v_mfma_f32_32x32x16_bf16 v[48:63], v[64:67], v[72:75], v[48:63]
	s_waitcnt lgkmcnt(3)
	v_mfma_f32_32x32x16_bf16 v[32:47], v[64:67], v[126:129], v[32:47]
	s_waitcnt lgkmcnt(2)
	v_mfma_f32_32x32x16_bf16 v[78:93], v[64:67], v[152:155], v[78:93]
	s_waitcnt lgkmcnt(1)
	v_mfma_f32_32x32x16_bf16 v[94:109], v[64:67], v[160:163], v[94:109]
	ds_read_b128 v[64:67], v156 offset:0
	s_waitcnt lgkmcnt(1)
	v_mfma_f32_32x32x16_bf16 v[132:147], v[68:71], v[160:163], v[132:147]
	ds_read_b128 v[160:163], v164 offset:18432
	v_mfma_f32_32x32x16_bf16 v[110:125], v[68:71], v[152:155], v[110:125]
	ds_read_b128 v[152:155], v164 offset:16384
	v_mfma_f32_32x32x16_bf16 v[0:15], v[68:71], v[126:129], v[0:15]
	ds_read_b128 v[126:129], v164 offset:10240
	v_mfma_f32_32x32x16_bf16 v[16:31], v[68:71], v[72:75], v[16:31]
	ds_read_b128 v[72:75], v164 offset:8192
	ds_read_b128 v[68:71], v156 offset:2048
	s_waitcnt lgkmcnt(4)
	v_mfma_f32_32x32x16_bf16 v[94:109], v[64:67], v[160:163], v[94:109]
	s_waitcnt lgkmcnt(3)
	v_mfma_f32_32x32x16_bf16 v[78:93], v[64:67], v[152:155], v[78:93]
	s_waitcnt lgkmcnt(2)
	v_mfma_f32_32x32x16_bf16 v[32:47], v[64:67], v[126:129], v[32:47]
	s_waitcnt lgkmcnt(1)
	v_mfma_f32_32x32x16_bf16 v[48:63], v[64:67], v[72:75], v[48:63]
	s_waitcnt vmcnt(0) lgkmcnt(0)
	s_barrier
	ds_read_b128 v[64:67], v151 offset:24576
	v_mfma_f32_32x32x16_bf16 v[16:31], v[68:71], v[72:75], v[16:31]
	ds_read_b128 v[72:75], v157 offset:32768
	v_mfma_f32_32x32x16_bf16 v[0:15], v[68:71], v[126:129], v[0:15]
	ds_read_b128 v[126:129], v157 offset:34816
	v_mfma_f32_32x32x16_bf16 v[110:125], v[68:71], v[152:155], v[110:125]
	ds_read_b128 v[152:155], v157 offset:41984
	v_mfma_f32_32x32x16_bf16 v[132:147], v[68:71], v[160:163], v[132:147]
	ds_read_b128 v[160:163], v157 offset:44032
	ds_read_b128 v[68:71], v151 offset:26624
	s_waitcnt lgkmcnt(4)
	v_mfma_f32_32x32x16_bf16 v[48:63], v[64:67], v[72:75], v[48:63]
	s_waitcnt lgkmcnt(3)
	v_mfma_f32_32x32x16_bf16 v[32:47], v[64:67], v[126:129], v[32:47]
	s_waitcnt lgkmcnt(2)
	v_mfma_f32_32x32x16_bf16 v[78:93], v[64:67], v[152:155], v[78:93]
	s_waitcnt lgkmcnt(1)
	v_mfma_f32_32x32x16_bf16 v[94:109], v[64:67], v[160:163], v[94:109]
	ds_read_b128 v[64:67], v156 offset:24576
	s_waitcnt lgkmcnt(1)
	v_mfma_f32_32x32x16_bf16 v[132:147], v[68:71], v[160:163], v[132:147]
	ds_read_b128 v[160:163], v164 offset:44032
	v_mfma_f32_32x32x16_bf16 v[110:125], v[68:71], v[152:155], v[110:125]
	ds_read_b128 v[152:155], v164 offset:41984
	v_mfma_f32_32x32x16_bf16 v[0:15], v[68:71], v[126:129], v[0:15]
	ds_read_b128 v[126:129], v164 offset:34816
	v_mfma_f32_32x32x16_bf16 v[16:31], v[68:71], v[72:75], v[16:31]
	ds_read_b128 v[72:75], v164 offset:32768
	ds_read_b128 v[68:71], v156 offset:26624
	s_waitcnt lgkmcnt(4)
	v_mfma_f32_32x32x16_bf16 v[94:109], v[64:67], v[160:163], v[94:109]
	s_waitcnt lgkmcnt(3)
	v_mfma_f32_32x32x16_bf16 v[78:93], v[64:67], v[152:155], v[78:93]
	s_waitcnt lgkmcnt(2)
	v_mfma_f32_32x32x16_bf16 v[32:47], v[64:67], v[126:129], v[32:47]
	s_waitcnt lgkmcnt(1)
	v_mfma_f32_32x32x16_bf16 v[48:63], v[64:67], v[72:75], v[48:63]
	s_waitcnt lgkmcnt(0)
	v_mfma_f32_32x32x16_bf16 v[16:31], v[68:71], v[72:75], v[16:31]
	v_mfma_f32_32x32x16_bf16 v[0:15], v[68:71], v[126:129], v[0:15]
	v_mfma_f32_32x32x16_bf16 v[110:125], v[68:71], v[152:155], v[110:125]
	v_mfma_f32_32x32x16_bf16 v[132:147], v[68:71], v[160:163], v[132:147]
	s_nop 7
	s_nop 7
	s_mov_b32 s32, 0
	s_lshl_b32 s9, s30, 7
	s_mov_b32 s10, s31

.Lg3a_cont:
	s_lshl3_add_u32 s22, s12, s25
	s_lshl_b32 s23, s13, 1
	s_mul_i32 s8, s22, 0x40000
	s_add_u32 s14, s44, s8
	s_addc_u32 s15, s45, 0
	s_mul_i32 s8, s23, 0x40000
	s_add_u32 s8, s8, 0xd80000
	s_add_u32 s16, s48, s8
	s_addc_u32 s17, s49, 0
	s_add_u32 s18, s16, 0x40000
	s_addc_u32 s19, s17, 0
	s_lshl_b32 s8, s22, 9
	s_add_u32 s30, s4, s8
	s_addc_u32 s31, s5, 0
	s_waitcnt vmcnt(0) lgkmcnt(0)
	s_barrier
	v_and_b32_e32 v167, 63, v148
	v_lshlrev_b32_e32 v167, 4, v167
	s_mov_b32 m0, 0xc400
	s_mov_b64 exec, 0xffffffff
	global_load_lds_dwordx4 v167, s[30:31]
	s_mov_b64 exec, -1
	s_add_u32 m0, s20, 0x0
	s_nop 0
	global_load_lds_dwordx4 v164, s[14:15]
	global_load_lds_dwordx4 v164, s[14:15] offset:1024
	s_add_u32 s14, s14, 0x2000
	s_addc_u32 s15, s15, 0
	s_add_u32 m0, s20, 0x2000
	s_nop 0
	global_load_lds_dwordx4 v164, s[16:17]
	global_load_lds_dwordx4 v164, s[16:17] offset:1024
	s_add_u32 s16, s16, 0x2000
	s_addc_u32 s17, s17, 0
	s_add_u32 m0, s20, 0x4000
	s_nop 0
	global_load_lds_dwordx4 v164, s[18:19]
	global_load_lds_dwordx4 v164, s[18:19] offset:1024
	s_add_u32 s18, s18, 0x2000
	s_addc_u32 s19, s19, 0
	s_waitcnt vmcnt(0)
	s_barrier
	s_add_u32 m0, s20, 0x6000
	s_nop 0
	global_load_lds_dwordx4 v164, s[14:15]
	global_load_lds_dwordx4 v164, s[14:15] offset:1024
	s_add_u32 s14, s14, 0x2000
	s_addc_u32 s15, s15, 0
	s_add_u32 m0, s20, 0x8000
	s_nop 0
	global_load_lds_dwordx4 v164, s[16:17]
	global_load_lds_dwordx4 v164, s[16:17] offset:1024
	s_add_u32 s16, s16, 0x2000
	s_addc_u32 s17, s17, 0
	s_add_u32 m0, s20, 0xa400
	s_nop 0
	global_load_lds_dwordx4 v164, s[18:19]
	global_load_lds_dwordx4 v164, s[18:19] offset:1024
	s_add_u32 s18, s18, 0x2000
	s_addc_u32 s19, s19, 0
	ds_read_b128 v[82:85], v160 offset:0
	ds_read_b128 v[138:141], v162 offset:8192
	ds_read_b128 v[142:145], v162 offset:10240
	ds_read_b128 v[150:153], v162 offset:16384
	ds_read_b128 v[154:157], v162 offset:18432
	ds_read_b128 v[134:137], v160 offset:2048
	s_waitcnt lgkmcnt(4)
	v_mfma_f32_32x32x16_bf16 v[32:47], v[82:85], v[138:141], 0
	s_waitcnt lgkmcnt(3)
	v_mfma_f32_32x32x16_bf16 v[48:63], v[82:85], v[142:145], 0
	s_waitcnt lgkmcnt(2)
	v_mfma_f32_32x32x16_bf16 v[86:101], v[82:85], v[150:153], 0
	s_waitcnt lgkmcnt(1)
	v_mfma_f32_32x32x16_bf16 v[102:117], v[82:85], v[154:157], 0
	ds_read_b128 v[82:85], v161 offset:0
	s_waitcnt lgkmcnt(1)
	v_mfma_f32_32x32x16_bf16 v[66:81], v[134:137], v[154:157], 0
	ds_read_b128 v[154:157], v163 offset:18432
	v_mfma_f32_32x32x16_bf16 v[118:133], v[134:137], v[150:153], 0
	ds_read_b128 v[150:153], v163 offset:16384
	v_mfma_f32_32x32x16_bf16 v[16:31], v[134:137], v[142:145], 0
	ds_read_b128 v[142:145], v163 offset:10240
	v_mfma_f32_32x32x16_bf16 v[0:15], v[134:137], v[138:141], 0
	ds_read_b128 v[138:141], v163 offset:8192
	ds_read_b128 v[134:137], v161 offset:2048
	s_waitcnt lgkmcnt(4)
	v_mfma_f32_32x32x16_bf16 v[102:117], v[82:85], v[154:157], v[102:117]
	s_waitcnt lgkmcnt(3)
	v_mfma_f32_32x32x16_bf16 v[86:101], v[82:85], v[150:153], v[86:101]
	s_waitcnt lgkmcnt(2)
	v_mfma_f32_32x32x16_bf16 v[48:63], v[82:85], v[142:145], v[48:63]
	s_waitcnt lgkmcnt(1)
	v_mfma_f32_32x32x16_bf16 v[32:47], v[82:85], v[138:141], v[32:47]
	s_setprio 2
	s_waitcnt vmcnt(0) lgkmcnt(0)
	s_barrier
	ds_read_b128 v[82:85], v160 offset:24576
	s_add_u32 m0, s20, 0x0
	s_nop 0
	global_load_lds_dwordx4 v164, s[14:15]
	global_load_lds_dwordx4 v164, s[14:15] offset:1024
	s_add_u32 s14, s14, 0x2000
	s_addc_u32 s15, s15, 0
	v_mfma_f32_32x32x16_bf16 v[0:15], v[134:137], v[138:141], v[0:15]
	ds_read_b128 v[138:141], v162 offset:32768
	s_add_u32 m0, s20, 0x2000
	s_nop 0
	global_load_lds_dwordx4 v164, s[16:17]
	global_load_lds_dwordx4 v164, s[16:17] offset:1024
	s_add_u32 s16, s16, 0x2000
	s_addc_u32 s17, s17, 0
	v_mfma_f32_32x32x16_bf16 v[16:31], v[134:137], v[142:145], v[16:31]
	ds_read_b128 v[142:145], v162 offset:34816
	s_add_u32 m0, s20, 0x4000
	s_nop 0
	global_load_lds_dwordx4 v164, s[18:19]
	global_load_lds_dwordx4 v164, s[18:19] offset:1024
	s_add_u32 s18, s18, 0x2000
	s_addc_u32 s19, s19, 0
	s_setprio 0
	v_mfma_f32_32x32x16_bf16 v[118:133], v[134:137], v[150:153], v[118:133]
	ds_read_b128 v[150:153], v162 offset:41984
	v_mfma_f32_32x32x16_bf16 v[66:81], v[134:137], v[154:157], v[66:81]
	ds_read_b128 v[154:157], v162 offset:44032
	ds_read_b128 v[134:137], v160 offset:26624
	s_waitcnt lgkmcnt(4)
	v_mfma_f32_32x32x16_bf16 v[32:47], v[82:85], v[138:141], v[32:47]
	s_waitcnt lgkmcnt(3)
	v_mfma_f32_32x32x16_bf16 v[48:63], v[82:85], v[142:145], v[48:63]
	s_waitcnt lgkmcnt(2)
	v_mfma_f32_32x32x16_bf16 v[86:101], v[82:85], v[150:153], v[86:101]
	s_waitcnt lgkmcnt(1)
	v_mfma_f32_32x32x16_bf16 v[102:117], v[82:85], v[154:157], v[102:117]
	ds_read_b128 v[82:85], v161 offset:24576
	s_waitcnt lgkmcnt(1)
	v_mfma_f32_32x32x16_bf16 v[66:81], v[134:137], v[154:157], v[66:81]
	ds_read_b128 v[154:157], v163 offset:44032
	v_mfma_f32_32x32x16_bf16 v[118:133], v[134:137], v[150:153], v[118:133]
	ds_read_b128 v[150:153], v163 offset:41984
	v_mfma_f32_32x32x16_bf16 v[16:31], v[134:137], v[142:145], v[16:31]
	ds_read_b128 v[142:145], v163 offset:34816
	v_mfma_f32_32x32x16_bf16 v[0:15], v[134:137], v[138:141], v[0:15]
	ds_read_b128 v[138:141], v163 offset:32768
	ds_read_b128 v[134:137], v161 offset:26624
	s_waitcnt lgkmcnt(4)
	v_mfma_f32_32x32x16_bf16 v[102:117], v[82:85], v[154:157], v[102:117]
	s_waitcnt lgkmcnt(3)
	v_mfma_f32_32x32x16_bf16 v[86:101], v[82:85], v[150:153], v[86:101]
	s_waitcnt lgkmcnt(2)
	v_mfma_f32_32x32x16_bf16 v[48:63], v[82:85], v[142:145], v[48:63]
	s_waitcnt lgkmcnt(1)
	v_mfma_f32_32x32x16_bf16 v[32:47], v[82:85], v[138:141], v[32:47]
	s_setprio 2
	s_waitcnt vmcnt(0) lgkmcnt(0)
	s_barrier
	ds_read_b128 v[82:85], v160 offset:0
	s_add_u32 m0, s20, 0x6000
	s_nop 0
	global_load_lds_dwordx4 v164, s[14:15]
	global_load_lds_dwordx4 v164, s[14:15] offset:1024
	s_add_u32 s14, s14, 0x2000
	s_addc_u32 s15, s15, 0
	v_mfma_f32_32x32x16_bf16 v[0:15], v[134:137], v[138:141], v[0:15]
	ds_read_b128 v[138:141], v162 offset:8192
	s_add_u32 m0, s20, 0x8000
	s_nop 0
	global_load_lds_dwordx4 v164, s[16:17]
	global_load_lds_dwordx4 v164, s[16:17] offset:1024
	s_add_u32 s16, s16, 0x2000
	s_addc_u32 s17, s17, 0
	v_mfma_f32_32x32x16_bf16 v[16:31], v[134:137], v[142:145], v[16:31]
	ds_read_b128 v[142:145], v162 offset:10240
	s_add_u32 m0, s20, 0xa400
	s_nop 0
	global_load_lds_dwordx4 v164, s[18:19]
	global_load_lds_dwordx4 v164, s[18:19] offset:1024
	s_add_u32 s18, s18, 0x2000
	s_addc_u32 s19, s19, 0
	s_setprio 0
	v_mfma_f32_32x32x16_bf16 v[118:133], v[134:137], v[150:153], v[118:133]
	ds_read_b128 v[150:153], v162 offset:16384
	v_mfma_f32_32x32x16_bf16 v[66:81], v[134:137], v[154:157], v[66:81]
	ds_read_b128 v[154:157], v162 offset:18432
	ds_read_b128 v[134:137], v160 offset:2048
	s_mov_b32 s21, 14
.Lg3a_kloop:
	s_waitcnt lgkmcnt(4)
	v_mfma_f32_32x32x16_bf16 v[32:47], v[82:85], v[138:141], v[32:47]
	s_waitcnt lgkmcnt(3)
	v_mfma_f32_32x32x16_bf16 v[48:63], v[82:85], v[142:145], v[48:63]
	s_waitcnt lgkmcnt(2)
	v_mfma_f32_32x32x16_bf16 v[86:101], v[82:85], v[150:153], v[86:101]
	s_waitcnt lgkmcnt(1)
	v_mfma_f32_32x32x16_bf16 v[102:117], v[82:85], v[154:157], v[102:117]
	ds_read_b128 v[82:85], v161 offset:0
	s_waitcnt lgkmcnt(1)
	v_mfma_f32_32x32x16_bf16 v[66:81], v[134:137], v[154:157], v[66:81]
	ds_read_b128 v[154:157], v163 offset:18432
	v_mfma_f32_32x32x16_bf16 v[118:133], v[134:137], v[150:153], v[118:133]
	ds_read_b128 v[150:153], v163 offset:16384
	v_mfma_f32_32x32x16_bf16 v[16:31], v[134:137], v[142:145], v[16:31]
	ds_read_b128 v[142:145], v163 offset:10240
	v_mfma_f32_32x32x16_bf16 v[0:15], v[134:137], v[138:141], v[0:15]
	ds_read_b128 v[138:141], v163 offset:8192
	ds_read_b128 v[134:137], v161 offset:2048
	s_waitcnt lgkmcnt(4)
	v_mfma_f32_32x32x16_bf16 v[102:117], v[82:85], v[154:157], v[102:117]
	s_waitcnt lgkmcnt(3)
	v_mfma_f32_32x32x16_bf16 v[86:101], v[82:85], v[150:153], v[86:101]
	s_waitcnt lgkmcnt(2)
	v_mfma_f32_32x32x16_bf16 v[48:63], v[82:85], v[142:145], v[48:63]
	s_waitcnt lgkmcnt(1)
	v_mfma_f32_32x32x16_bf16 v[32:47], v[82:85], v[138:141], v[32:47]
	s_setprio 2
	s_waitcnt vmcnt(0) lgkmcnt(0)
	s_barrier
	ds_read_b128 v[82:85], v160 offset:24576
	s_add_u32 m0, s20, 0x0
	s_nop 0
	global_load_lds_dwordx4 v164, s[14:15]
	global_load_lds_dwordx4 v164, s[14:15] offset:1024
	s_add_u32 s14, s14, 0x2000
	s_addc_u32 s15, s15, 0
	v_mfma_f32_32x32x16_bf16 v[0:15], v[134:137], v[138:141], v[0:15]
	ds_read_b128 v[138:141], v162 offset:32768
	s_add_u32 m0, s20, 0x2000
	s_nop 0
	global_load_lds_dwordx4 v164, s[16:17]
	global_load_lds_dwordx4 v164, s[16:17] offset:1024
	s_add_u32 s16, s16, 0x2000
	s_addc_u32 s17, s17, 0
	v_mfma_f32_32x32x16_bf16 v[16:31], v[134:137], v[142:145], v[16:31]
	ds_read_b128 v[142:145], v162 offset:34816
	s_add_u32 m0, s20, 0x4000
	s_nop 0
	global_load_lds_dwordx4 v164, s[18:19]
	global_load_lds_dwordx4 v164, s[18:19] offset:1024
	s_add_u32 s18, s18, 0x2000
	s_addc_u32 s19, s19, 0
	s_setprio 0
	v_mfma_f32_32x32x16_bf16 v[118:133], v[134:137], v[150:153], v[118:133]
	ds_read_b128 v[150:153], v162 offset:41984
	v_mfma_f32_32x32x16_bf16 v[66:81], v[134:137], v[154:157], v[66:81]
	ds_read_b128 v[154:157], v162 offset:44032
	ds_read_b128 v[134:137], v160 offset:26624
	s_waitcnt lgkmcnt(4)
	v_mfma_f32_32x32x16_bf16 v[32:47], v[82:85], v[138:141], v[32:47]
	s_waitcnt lgkmcnt(3)
	v_mfma_f32_32x32x16_bf16 v[48:63], v[82:85], v[142:145], v[48:63]
	s_waitcnt lgkmcnt(2)
	v_mfma_f32_32x32x16_bf16 v[86:101], v[82:85], v[150:153], v[86:101]
	s_waitcnt lgkmcnt(1)
	v_mfma_f32_32x32x16_bf16 v[102:117], v[82:85], v[154:157], v[102:117]
	ds_read_b128 v[82:85], v161 offset:24576
	s_waitcnt lgkmcnt(1)
	v_mfma_f32_32x32x16_bf16 v[66:81], v[134:137], v[154:157], v[66:81]
	ds_read_b128 v[154:157], v163 offset:44032
	v_mfma_f32_32x32x16_bf16 v[118:133], v[134:137], v[150:153], v[118:133]
	ds_read_b128 v[150:153], v163 offset:41984
	v_mfma_f32_32x32x16_bf16 v[16:31], v[134:137], v[142:145], v[16:31]
	ds_read_b128 v[142:145], v163 offset:34816
	v_mfma_f32_32x32x16_bf16 v[0:15], v[134:137], v[138:141], v[0:15]
	ds_read_b128 v[138:141], v163 offset:32768
	ds_read_b128 v[134:137], v161 offset:26624
	s_waitcnt lgkmcnt(4)
	v_mfma_f32_32x32x16_bf16 v[102:117], v[82:85], v[154:157], v[102:117]
	s_waitcnt lgkmcnt(3)
	v_mfma_f32_32x32x16_bf16 v[86:101], v[82:85], v[150:153], v[86:101]
	s_waitcnt lgkmcnt(2)
	v_mfma_f32_32x32x16_bf16 v[48:63], v[82:85], v[142:145], v[48:63]
	s_waitcnt lgkmcnt(1)
	v_mfma_f32_32x32x16_bf16 v[32:47], v[82:85], v[138:141], v[32:47]
	s_setprio 2
	s_waitcnt vmcnt(0) lgkmcnt(0)
	s_barrier
	ds_read_b128 v[82:85], v160 offset:0
	s_add_u32 m0, s20, 0x6000
	s_nop 0
	global_load_lds_dwordx4 v164, s[14:15]
	global_load_lds_dwordx4 v164, s[14:15] offset:1024
	s_add_u32 s14, s14, 0x2000
	s_addc_u32 s15, s15, 0
	v_mfma_f32_32x32x16_bf16 v[0:15], v[134:137], v[138:141], v[0:15]
	ds_read_b128 v[138:141], v162 offset:8192
	s_add_u32 m0, s20, 0x8000
	s_nop 0
	global_load_lds_dwordx4 v164, s[16:17]
	global_load_lds_dwordx4 v164, s[16:17] offset:1024
	s_add_u32 s16, s16, 0x2000
	s_addc_u32 s17, s17, 0
	v_mfma_f32_32x32x16_bf16 v[16:31], v[134:137], v[142:145], v[16:31]
	ds_read_b128 v[142:145], v162 offset:10240
	s_add_u32 m0, s20, 0xa400
	s_nop 0
	global_load_lds_dwordx4 v164, s[18:19]
	global_load_lds_dwordx4 v164, s[18:19] offset:1024
	s_add_u32 s18, s18, 0x2000
	s_addc_u32 s19, s19, 0
	s_setprio 0
	v_mfma_f32_32x32x16_bf16 v[118:133], v[134:137], v[150:153], v[118:133]
	ds_read_b128 v[150:153], v162 offset:16384
	v_mfma_f32_32x32x16_bf16 v[66:81], v[134:137], v[154:157], v[66:81]
	ds_read_b128 v[154:157], v162 offset:18432
	ds_read_b128 v[134:137], v160 offset:2048
	s_sub_u32 s21, s21, 1
	s_cmp_lg_u32 s21, 0
	s_cbranch_scc1 .Lg3a_kloop
	s_waitcnt lgkmcnt(4)
	v_mfma_f32_32x32x16_bf16 v[32:47], v[82:85], v[138:141], v[32:47]
	s_waitcnt lgkmcnt(3)
	v_mfma_f32_32x32x16_bf16 v[48:63], v[82:85], v[142:145], v[48:63]
	s_waitcnt lgkmcnt(2)
	v_mfma_f32_32x32x16_bf16 v[86:101], v[82:85], v[150:153], v[86:101]
	s_waitcnt lgkmcnt(1)
	v_mfma_f32_32x32x16_bf16 v[102:117], v[82:85], v[154:157], v[102:117]
	ds_read_b128 v[82:85], v161 offset:0
	s_waitcnt lgkmcnt(1)
	v_mfma_f32_32x32x16_bf16 v[66:81], v[134:137], v[154:157], v[66:81]
	ds_read_b128 v[154:157], v163 offset:18432
	v_mfma_f32_32x32x16_bf16 v[118:133], v[134:137], v[150:153], v[118:133]
	ds_read_b128 v[150:153], v163 offset:16384
	v_mfma_f32_32x32x16_bf16 v[16:31], v[134:137], v[142:145], v[16:31]
	ds_read_b128 v[142:145], v163 offset:10240
	v_mfma_f32_32x32x16_bf16 v[0:15], v[134:137], v[138:141], v[0:15]
	ds_read_b128 v[138:141], v163 offset:8192
	ds_read_b128 v[134:137], v161 offset:2048
	s_waitcnt lgkmcnt(4)
	v_mfma_f32_32x32x16_bf16 v[102:117], v[82:85], v[154:157], v[102:117]
	s_waitcnt lgkmcnt(3)
	v_mfma_f32_32x32x16_bf16 v[86:101], v[82:85], v[150:153], v[86:101]
	s_waitcnt lgkmcnt(2)
	v_mfma_f32_32x32x16_bf16 v[48:63], v[82:85], v[142:145], v[48:63]
	s_waitcnt lgkmcnt(1)
	v_mfma_f32_32x32x16_bf16 v[32:47], v[82:85], v[138:141], v[32:47]
	s_waitcnt vmcnt(0) lgkmcnt(0)
	s_barrier
	ds_read_b128 v[82:85], v160 offset:24576
	v_mfma_f32_32x32x16_bf16 v[0:15], v[134:137], v[138:141], v[0:15]
	ds_read_b128 v[138:141], v162 offset:32768
	v_mfma_f32_32x32x16_bf16 v[16:31], v[134:137], v[142:145], v[16:31]
	ds_read_b128 v[142:145], v162 offset:34816
	v_mfma_f32_32x32x16_bf16 v[118:133], v[134:137], v[150:153], v[118:133]
	ds_read_b128 v[150:153], v162 offset:41984
	v_mfma_f32_32x32x16_bf16 v[66:81], v[134:137], v[154:157], v[66:81]
	ds_read_b128 v[154:157], v162 offset:44032
	ds_read_b128 v[134:137], v160 offset:26624
	s_waitcnt lgkmcnt(4)
	v_mfma_f32_32x32x16_bf16 v[32:47], v[82:85], v[138:141], v[32:47]
	s_waitcnt lgkmcnt(3)
	v_mfma_f32_32x32x16_bf16 v[48:63], v[82:85], v[142:145], v[48:63]
	s_waitcnt lgkmcnt(2)
	v_mfma_f32_32x32x16_bf16 v[86:101], v[82:85], v[150:153], v[86:101]
	s_waitcnt lgkmcnt(1)
	v_mfma_f32_32x32x16_bf16 v[102:117], v[82:85], v[154:157], v[102:117]
	ds_read_b128 v[82:85], v161 offset:24576
	s_waitcnt lgkmcnt(1)
	v_mfma_f32_32x32x16_bf16 v[66:81], v[134:137], v[154:157], v[66:81]
	ds_read_b128 v[154:157], v163 offset:44032
	v_mfma_f32_32x32x16_bf16 v[118:133], v[134:137], v[150:153], v[118:133]
	ds_read_b128 v[150:153], v163 offset:41984
	v_mfma_f32_32x32x16_bf16 v[16:31], v[134:137], v[142:145], v[16:31]
	ds_read_b128 v[142:145], v163 offset:34816
	v_mfma_f32_32x32x16_bf16 v[0:15], v[134:137], v[138:141], v[0:15]
	ds_read_b128 v[138:141], v163 offset:32768
	ds_read_b128 v[134:137], v161 offset:26624
	s_waitcnt lgkmcnt(4)
	v_mfma_f32_32x32x16_bf16 v[102:117], v[82:85], v[154:157], v[102:117]
	s_waitcnt lgkmcnt(3)
	v_mfma_f32_32x32x16_bf16 v[86:101], v[82:85], v[150:153], v[86:101]
	s_waitcnt lgkmcnt(2)
	v_mfma_f32_32x32x16_bf16 v[48:63], v[82:85], v[142:145], v[48:63]
	s_waitcnt lgkmcnt(1)
	v_mfma_f32_32x32x16_bf16 v[32:47], v[82:85], v[138:141], v[32:47]
	s_waitcnt lgkmcnt(0)
	v_mfma_f32_32x32x16_bf16 v[0:15], v[134:137], v[138:141], v[0:15]
	v_mfma_f32_32x32x16_bf16 v[16:31], v[134:137], v[142:145], v[16:31]
	v_mfma_f32_32x32x16_bf16 v[118:133], v[134:137], v[150:153], v[118:133]
	v_mfma_f32_32x32x16_bf16 v[66:81], v[134:137], v[154:157], v[66:81]
	s_nop 7
	s_nop 7
	v_mov_b32_e32 v134, v73
	v_mov_b32_e32 v135, v74
	v_mov_b32_e32 v136, v75
	v_mov_b32_e32 v137, v76
	v_mov_b32_e32 v138, v77
	v_mov_b32_e32 v139, v78
	v_mov_b32_e32 v140, v79
	s_mov_b32 s24, 0
	s_mov_b32 s0, s22
	s_mov_b32 s10, s23

.Lg4a_cont:
	s_lshl3_add_u32 s30, s3, s33
	s_lshl_b32 s31, s4, 1
	s_mul_i32 s0, s30, 0xb0000
	s_add_u32 s22, s46, s0
	s_addc_u32 s23, s47, 0
	s_mul_i32 s0, s31, 0xb0000
	s_add_u32 s0, s0, 0x1880000
	s_add_u32 s24, s48, s0
	s_addc_u32 s25, s49, 0
	s_add_u32 s26, s24, 0xb0000
	s_addc_u32 s27, s25, 0
	s_waitcnt vmcnt(0) lgkmcnt(0)
	s_barrier
	s_add_u32 m0, s28, 0x0
	s_nop 0
	global_load_lds_dwordx4 v157, s[22:23]
	global_load_lds_dwordx4 v157, s[22:23] offset:1024
	s_add_u32 s22, s22, 0x2000
	s_addc_u32 s23, s23, 0
	s_add_u32 m0, s28, 0x2000
	s_nop 0
	global_load_lds_dwordx4 v157, s[24:25]
	global_load_lds_dwordx4 v157, s[24:25] offset:1024
	s_add_u32 s24, s24, 0x2000
	s_addc_u32 s25, s25, 0
	s_add_u32 m0, s28, 0x4000
	s_nop 0
	global_load_lds_dwordx4 v157, s[26:27]
	global_load_lds_dwordx4 v157, s[26:27] offset:1024
	s_add_u32 s26, s26, 0x2000
	s_addc_u32 s27, s27, 0
	s_waitcnt vmcnt(0)
	s_barrier
	s_add_u32 m0, s28, 0x6000
	s_nop 0
	global_load_lds_dwordx4 v157, s[22:23]
	global_load_lds_dwordx4 v157, s[22:23] offset:1024
	s_add_u32 s22, s22, 0x2000
	s_addc_u32 s23, s23, 0
	s_add_u32 m0, s28, 0x8000
	s_nop 0
	global_load_lds_dwordx4 v157, s[24:25]
	global_load_lds_dwordx4 v157, s[24:25] offset:1024
	s_add_u32 s24, s24, 0x2000
	s_addc_u32 s25, s25, 0
	s_add_u32 m0, s28, 0xa400
	s_nop 0
	global_load_lds_dwordx4 v157, s[26:27]
	global_load_lds_dwordx4 v157, s[26:27] offset:1024
	s_add_u32 s26, s26, 0x2000
	s_addc_u32 s27, s27, 0
	ds_read_b128 v[130:133], v81 offset:0
	ds_read_b128 v[138:141], v146 offset:8192
	ds_read_b128 v[150:153], v146 offset:10240
	ds_read_b128 v[160:163], v146 offset:16384
	ds_read_b128 v[164:167], v146 offset:18432
	ds_read_b128 v[134:137], v81 offset:2048
	s_waitcnt lgkmcnt(4)
	v_mfma_f32_32x32x16_bf16 v[64:79], v[130:133], v[138:141], 0
	s_waitcnt lgkmcnt(3)
	v_mfma_f32_32x32x16_bf16 v[48:63], v[130:133], v[150:153], 0
	s_waitcnt lgkmcnt(2)
	v_mfma_f32_32x32x16_bf16 v[82:97], v[130:133], v[160:163], 0
	s_waitcnt lgkmcnt(1)
	v_mfma_f32_32x32x16_bf16 v[98:113], v[130:133], v[164:167], 0
	ds_read_b128 v[130:133], v145 offset:0
	s_waitcnt lgkmcnt(1)
	v_mfma_f32_32x32x16_bf16 v[0:15], v[134:137], v[164:167], 0
	ds_read_b128 v[164:167], v147 offset:18432
	v_mfma_f32_32x32x16_bf16 v[114:129], v[134:137], v[160:163], 0
	ds_read_b128 v[160:163], v147 offset:16384
	v_mfma_f32_32x32x16_bf16 v[16:31], v[134:137], v[150:153], 0
	ds_read_b128 v[150:153], v147 offset:10240
	v_mfma_f32_32x32x16_bf16 v[32:47], v[134:137], v[138:141], 0
	ds_read_b128 v[138:141], v147 offset:8192
	ds_read_b128 v[134:137], v145 offset:2048
	s_waitcnt lgkmcnt(4)
	v_mfma_f32_32x32x16_bf16 v[98:113], v[130:133], v[164:167], v[98:113]
	s_waitcnt lgkmcnt(3)
	v_mfma_f32_32x32x16_bf16 v[82:97], v[130:133], v[160:163], v[82:97]
	s_waitcnt lgkmcnt(2)
	v_mfma_f32_32x32x16_bf16 v[48:63], v[130:133], v[150:153], v[48:63]
	s_waitcnt lgkmcnt(1)
	v_mfma_f32_32x32x16_bf16 v[64:79], v[130:133], v[138:141], v[64:79]
	s_setprio 2
	s_waitcnt vmcnt(0) lgkmcnt(0)
	s_barrier
	ds_read_b128 v[130:133], v81 offset:24576
	s_add_u32 m0, s28, 0x0
	s_nop 0
	global_load_lds_dwordx4 v157, s[22:23]
	global_load_lds_dwordx4 v157, s[22:23] offset:1024
	s_add_u32 s22, s22, 0x2000
	s_addc_u32 s23, s23, 0
	v_mfma_f32_32x32x16_bf16 v[32:47], v[134:137], v[138:141], v[32:47]
	ds_read_b128 v[138:141], v146 offset:32768
	s_add_u32 m0, s28, 0x2000
	s_nop 0
	global_load_lds_dwordx4 v157, s[24:25]
	global_load_lds_dwordx4 v157, s[24:25] offset:1024
	s_add_u32 s24, s24, 0x2000
	s_addc_u32 s25, s25, 0
	v_mfma_f32_32x32x16_bf16 v[16:31], v[134:137], v[150:153], v[16:31]
	ds_read_b128 v[150:153], v146 offset:34816
	s_add_u32 m0, s28, 0x4000
	s_nop 0
	global_load_lds_dwordx4 v157, s[26:27]
	global_load_lds_dwordx4 v157, s[26:27] offset:1024
	s_add_u32 s26, s26, 0x2000
	s_addc_u32 s27, s27, 0
	s_setprio 0
	v_mfma_f32_32x32x16_bf16 v[114:129], v[134:137], v[160:163], v[114:129]
	ds_read_b128 v[160:163], v146 offset:41984
	v_mfma_f32_32x32x16_bf16 v[0:15], v[134:137], v[164:167], v[0:15]
	ds_read_b128 v[164:167], v146 offset:44032
	ds_read_b128 v[134:137], v81 offset:26624
	s_waitcnt lgkmcnt(4)
	v_mfma_f32_32x32x16_bf16 v[64:79], v[130:133], v[138:141], v[64:79]
	s_waitcnt lgkmcnt(3)
	v_mfma_f32_32x32x16_bf16 v[48:63], v[130:133], v[150:153], v[48:63]
	s_waitcnt lgkmcnt(2)
	v_mfma_f32_32x32x16_bf16 v[82:97], v[130:133], v[160:163], v[82:97]
	s_waitcnt lgkmcnt(1)
	v_mfma_f32_32x32x16_bf16 v[98:113], v[130:133], v[164:167], v[98:113]
	ds_read_b128 v[130:133], v145 offset:24576
	s_waitcnt lgkmcnt(1)
	v_mfma_f32_32x32x16_bf16 v[0:15], v[134:137], v[164:167], v[0:15]
	ds_read_b128 v[164:167], v147 offset:44032
	v_mfma_f32_32x32x16_bf16 v[114:129], v[134:137], v[160:163], v[114:129]
	ds_read_b128 v[160:163], v147 offset:41984
	v_mfma_f32_32x32x16_bf16 v[16:31], v[134:137], v[150:153], v[16:31]
	ds_read_b128 v[150:153], v147 offset:34816
	v_mfma_f32_32x32x16_bf16 v[32:47], v[134:137], v[138:141], v[32:47]
	ds_read_b128 v[138:141], v147 offset:32768
	ds_read_b128 v[134:137], v145 offset:26624
	s_waitcnt lgkmcnt(4)
	v_mfma_f32_32x32x16_bf16 v[98:113], v[130:133], v[164:167], v[98:113]
	s_waitcnt lgkmcnt(3)
	v_mfma_f32_32x32x16_bf16 v[82:97], v[130:133], v[160:163], v[82:97]
	s_waitcnt lgkmcnt(2)
	v_mfma_f32_32x32x16_bf16 v[48:63], v[130:133], v[150:153], v[48:63]
	s_waitcnt lgkmcnt(1)
	v_mfma_f32_32x32x16_bf16 v[64:79], v[130:133], v[138:141], v[64:79]
	s_setprio 2
	s_waitcnt vmcnt(0) lgkmcnt(0)
	s_barrier
	ds_read_b128 v[130:133], v81 offset:0
	s_add_u32 m0, s28, 0x6000
	s_nop 0
	global_load_lds_dwordx4 v157, s[22:23]
	global_load_lds_dwordx4 v157, s[22:23] offset:1024
	s_add_u32 s22, s22, 0x2000
	s_addc_u32 s23, s23, 0
	v_mfma_f32_32x32x16_bf16 v[32:47], v[134:137], v[138:141], v[32:47]
	ds_read_b128 v[138:141], v146 offset:8192
	s_add_u32 m0, s28, 0x8000
	s_nop 0
	global_load_lds_dwordx4 v157, s[24:25]
	global_load_lds_dwordx4 v157, s[24:25] offset:1024
	s_add_u32 s24, s24, 0x2000
	s_addc_u32 s25, s25, 0
	v_mfma_f32_32x32x16_bf16 v[16:31], v[134:137], v[150:153], v[16:31]
	ds_read_b128 v[150:153], v146 offset:10240
	s_add_u32 m0, s28, 0xa400
	s_nop 0
	global_load_lds_dwordx4 v157, s[26:27]
	global_load_lds_dwordx4 v157, s[26:27] offset:1024
	s_add_u32 s26, s26, 0x2000
	s_addc_u32 s27, s27, 0
	s_setprio 0
	v_mfma_f32_32x32x16_bf16 v[114:129], v[134:137], v[160:163], v[114:129]
	ds_read_b128 v[160:163], v146 offset:16384
	v_mfma_f32_32x32x16_bf16 v[0:15], v[134:137], v[164:167], v[0:15]
	ds_read_b128 v[164:167], v146 offset:18432
	ds_read_b128 v[134:137], v81 offset:2048
	s_mov_b32 s29, 42
.Lg4a_kloop:
	s_waitcnt lgkmcnt(4)
	v_mfma_f32_32x32x16_bf16 v[64:79], v[130:133], v[138:141], v[64:79]
	s_waitcnt lgkmcnt(3)
	v_mfma_f32_32x32x16_bf16 v[48:63], v[130:133], v[150:153], v[48:63]
	s_waitcnt lgkmcnt(2)
	v_mfma_f32_32x32x16_bf16 v[82:97], v[130:133], v[160:163], v[82:97]
	s_waitcnt lgkmcnt(1)
	v_mfma_f32_32x32x16_bf16 v[98:113], v[130:133], v[164:167], v[98:113]
	ds_read_b128 v[130:133], v145 offset:0
	s_waitcnt lgkmcnt(1)
	v_mfma_f32_32x32x16_bf16 v[0:15], v[134:137], v[164:167], v[0:15]
	ds_read_b128 v[164:167], v147 offset:18432
	v_mfma_f32_32x32x16_bf16 v[114:129], v[134:137], v[160:163], v[114:129]
	ds_read_b128 v[160:163], v147 offset:16384
	v_mfma_f32_32x32x16_bf16 v[16:31], v[134:137], v[150:153], v[16:31]
	ds_read_b128 v[150:153], v147 offset:10240
	v_mfma_f32_32x32x16_bf16 v[32:47], v[134:137], v[138:141], v[32:47]
	ds_read_b128 v[138:141], v147 offset:8192
	ds_read_b128 v[134:137], v145 offset:2048
	s_waitcnt lgkmcnt(4)
	v_mfma_f32_32x32x16_bf16 v[98:113], v[130:133], v[164:167], v[98:113]
	s_waitcnt lgkmcnt(3)
	v_mfma_f32_32x32x16_bf16 v[82:97], v[130:133], v[160:163], v[82:97]
	s_waitcnt lgkmcnt(2)
	v_mfma_f32_32x32x16_bf16 v[48:63], v[130:133], v[150:153], v[48:63]
	s_waitcnt lgkmcnt(1)
	v_mfma_f32_32x32x16_bf16 v[64:79], v[130:133], v[138:141], v[64:79]
	s_setprio 2
	s_waitcnt vmcnt(0) lgkmcnt(0)
	s_barrier
	ds_read_b128 v[130:133], v81 offset:24576
	s_add_u32 m0, s28, 0x0
	s_nop 0
	global_load_lds_dwordx4 v157, s[22:23]
	global_load_lds_dwordx4 v157, s[22:23] offset:1024
	s_add_u32 s22, s22, 0x2000
	s_addc_u32 s23, s23, 0
	v_mfma_f32_32x32x16_bf16 v[32:47], v[134:137], v[138:141], v[32:47]
	ds_read_b128 v[138:141], v146 offset:32768
	s_add_u32 m0, s28, 0x2000
	s_nop 0
	global_load_lds_dwordx4 v157, s[24:25]
	global_load_lds_dwordx4 v157, s[24:25] offset:1024
	s_add_u32 s24, s24, 0x2000
	s_addc_u32 s25, s25, 0
	v_mfma_f32_32x32x16_bf16 v[16:31], v[134:137], v[150:153], v[16:31]
	ds_read_b128 v[150:153], v146 offset:34816
	s_add_u32 m0, s28, 0x4000
	s_nop 0
	global_load_lds_dwordx4 v157, s[26:27]
	global_load_lds_dwordx4 v157, s[26:27] offset:1024
	s_add_u32 s26, s26, 0x2000
	s_addc_u32 s27, s27, 0
	s_setprio 0
	v_mfma_f32_32x32x16_bf16 v[114:129], v[134:137], v[160:163], v[114:129]
	ds_read_b128 v[160:163], v146 offset:41984
	v_mfma_f32_32x32x16_bf16 v[0:15], v[134:137], v[164:167], v[0:15]
	ds_read_b128 v[164:167], v146 offset:44032
	ds_read_b128 v[134:137], v81 offset:26624
	s_waitcnt lgkmcnt(4)
	v_mfma_f32_32x32x16_bf16 v[64:79], v[130:133], v[138:141], v[64:79]
	s_waitcnt lgkmcnt(3)
	v_mfma_f32_32x32x16_bf16 v[48:63], v[130:133], v[150:153], v[48:63]
	s_waitcnt lgkmcnt(2)
	v_mfma_f32_32x32x16_bf16 v[82:97], v[130:133], v[160:163], v[82:97]
	s_waitcnt lgkmcnt(1)
	v_mfma_f32_32x32x16_bf16 v[98:113], v[130:133], v[164:167], v[98:113]
	ds_read_b128 v[130:133], v145 offset:24576
	s_waitcnt lgkmcnt(1)
	v_mfma_f32_32x32x16_bf16 v[0:15], v[134:137], v[164:167], v[0:15]
	ds_read_b128 v[164:167], v147 offset:44032
	v_mfma_f32_32x32x16_bf16 v[114:129], v[134:137], v[160:163], v[114:129]
	ds_read_b128 v[160:163], v147 offset:41984
	v_mfma_f32_32x32x16_bf16 v[16:31], v[134:137], v[150:153], v[16:31]
	ds_read_b128 v[150:153], v147 offset:34816
	v_mfma_f32_32x32x16_bf16 v[32:47], v[134:137], v[138:141], v[32:47]
	ds_read_b128 v[138:141], v147 offset:32768
	ds_read_b128 v[134:137], v145 offset:26624
	s_waitcnt lgkmcnt(4)
	v_mfma_f32_32x32x16_bf16 v[98:113], v[130:133], v[164:167], v[98:113]
	s_waitcnt lgkmcnt(3)
	v_mfma_f32_32x32x16_bf16 v[82:97], v[130:133], v[160:163], v[82:97]
	s_waitcnt lgkmcnt(2)
	v_mfma_f32_32x32x16_bf16 v[48:63], v[130:133], v[150:153], v[48:63]
	s_waitcnt lgkmcnt(1)
	v_mfma_f32_32x32x16_bf16 v[64:79], v[130:133], v[138:141], v[64:79]
	s_setprio 2
	s_waitcnt vmcnt(0) lgkmcnt(0)
	s_barrier
	ds_read_b128 v[130:133], v81 offset:0
	s_add_u32 m0, s28, 0x6000
	s_nop 0
	global_load_lds_dwordx4 v157, s[22:23]
	global_load_lds_dwordx4 v157, s[22:23] offset:1024
	s_add_u32 s22, s22, 0x2000
	s_addc_u32 s23, s23, 0
	v_mfma_f32_32x32x16_bf16 v[32:47], v[134:137], v[138:141], v[32:47]
	ds_read_b128 v[138:141], v146 offset:8192
	s_add_u32 m0, s28, 0x8000
	s_nop 0
	global_load_lds_dwordx4 v157, s[24:25]
	global_load_lds_dwordx4 v157, s[24:25] offset:1024
	s_add_u32 s24, s24, 0x2000
	s_addc_u32 s25, s25, 0
	v_mfma_f32_32x32x16_bf16 v[16:31], v[134:137], v[150:153], v[16:31]
	ds_read_b128 v[150:153], v146 offset:10240
	s_add_u32 m0, s28, 0xa400
	s_nop 0
	global_load_lds_dwordx4 v157, s[26:27]
	global_load_lds_dwordx4 v157, s[26:27] offset:1024
	s_add_u32 s26, s26, 0x2000
	s_addc_u32 s27, s27, 0
	s_setprio 0
	v_mfma_f32_32x32x16_bf16 v[114:129], v[134:137], v[160:163], v[114:129]
	ds_read_b128 v[160:163], v146 offset:16384
	v_mfma_f32_32x32x16_bf16 v[0:15], v[134:137], v[164:167], v[0:15]
	ds_read_b128 v[164:167], v146 offset:18432
	ds_read_b128 v[134:137], v81 offset:2048
	s_sub_u32 s29, s29, 1
	s_cmp_lg_u32 s29, 0
	s_cbranch_scc1 .Lg4a_kloop
	s_waitcnt lgkmcnt(4)
	v_mfma_f32_32x32x16_bf16 v[64:79], v[130:133], v[138:141], v[64:79]
	s_waitcnt lgkmcnt(3)
	v_mfma_f32_32x32x16_bf16 v[48:63], v[130:133], v[150:153], v[48:63]
	s_waitcnt lgkmcnt(2)
	v_mfma_f32_32x32x16_bf16 v[82:97], v[130:133], v[160:163], v[82:97]
	s_waitcnt lgkmcnt(1)
	v_mfma_f32_32x32x16_bf16 v[98:113], v[130:133], v[164:167], v[98:113]
	ds_read_b128 v[130:133], v145 offset:0
	s_waitcnt lgkmcnt(1)
	v_mfma_f32_32x32x16_bf16 v[0:15], v[134:137], v[164:167], v[0:15]
	ds_read_b128 v[164:167], v147 offset:18432
	v_mfma_f32_32x32x16_bf16 v[114:129], v[134:137], v[160:163], v[114:129]
	ds_read_b128 v[160:163], v147 offset:16384
	v_mfma_f32_32x32x16_bf16 v[16:31], v[134:137], v[150:153], v[16:31]
	ds_read_b128 v[150:153], v147 offset:10240
	v_mfma_f32_32x32x16_bf16 v[32:47], v[134:137], v[138:141], v[32:47]
	ds_read_b128 v[138:141], v147 offset:8192
	ds_read_b128 v[134:137], v145 offset:2048
	s_waitcnt lgkmcnt(4)
	v_mfma_f32_32x32x16_bf16 v[98:113], v[130:133], v[164:167], v[98:113]
	s_waitcnt lgkmcnt(3)
	v_mfma_f32_32x32x16_bf16 v[82:97], v[130:133], v[160:163], v[82:97]
	s_waitcnt lgkmcnt(2)
	v_mfma_f32_32x32x16_bf16 v[48:63], v[130:133], v[150:153], v[48:63]
	s_waitcnt lgkmcnt(1)
	v_mfma_f32_32x32x16_bf16 v[64:79], v[130:133], v[138:141], v[64:79]
	s_waitcnt vmcnt(0) lgkmcnt(0)
	s_barrier
	ds_read_b128 v[130:133], v81 offset:24576
	v_mfma_f32_32x32x16_bf16 v[32:47], v[134:137], v[138:141], v[32:47]
	ds_read_b128 v[138:141], v146 offset:32768
	v_mfma_f32_32x32x16_bf16 v[16:31], v[134:137], v[150:153], v[16:31]
	ds_read_b128 v[150:153], v146 offset:34816
	v_mfma_f32_32x32x16_bf16 v[114:129], v[134:137], v[160:163], v[114:129]
	ds_read_b128 v[160:163], v146 offset:41984
	v_mfma_f32_32x32x16_bf16 v[0:15], v[134:137], v[164:167], v[0:15]
	ds_read_b128 v[164:167], v146 offset:44032
	ds_read_b128 v[134:137], v81 offset:26624
	s_waitcnt lgkmcnt(4)
	v_mfma_f32_32x32x16_bf16 v[64:79], v[130:133], v[138:141], v[64:79]
	s_waitcnt lgkmcnt(3)
	v_mfma_f32_32x32x16_bf16 v[48:63], v[130:133], v[150:153], v[48:63]
	s_waitcnt lgkmcnt(2)
	v_mfma_f32_32x32x16_bf16 v[82:97], v[130:133], v[160:163], v[82:97]
	s_waitcnt lgkmcnt(1)
	v_mfma_f32_32x32x16_bf16 v[98:113], v[130:133], v[164:167], v[98:113]
	ds_read_b128 v[130:133], v145 offset:24576
	s_waitcnt lgkmcnt(1)
	v_mfma_f32_32x32x16_bf16 v[0:15], v[134:137], v[164:167], v[0:15]
	ds_read_b128 v[164:167], v147 offset:44032
	v_mfma_f32_32x32x16_bf16 v[114:129], v[134:137], v[160:163], v[114:129]
	ds_read_b128 v[160:163], v147 offset:41984
	v_mfma_f32_32x32x16_bf16 v[16:31], v[134:137], v[150:153], v[16:31]
	ds_read_b128 v[150:153], v147 offset:34816
	v_mfma_f32_32x32x16_bf16 v[32:47], v[134:137], v[138:141], v[32:47]
	ds_read_b128 v[138:141], v147 offset:32768
	ds_read_b128 v[134:137], v145 offset:26624
	s_waitcnt lgkmcnt(4)
	v_mfma_f32_32x32x16_bf16 v[98:113], v[130:133], v[164:167], v[98:113]
	s_waitcnt lgkmcnt(3)
	v_mfma_f32_32x32x16_bf16 v[82:97], v[130:133], v[160:163], v[82:97]
	s_waitcnt lgkmcnt(2)
	v_mfma_f32_32x32x16_bf16 v[48:63], v[130:133], v[150:153], v[48:63]
	s_waitcnt lgkmcnt(1)
	v_mfma_f32_32x32x16_bf16 v[64:79], v[130:133], v[138:141], v[64:79]
	s_waitcnt lgkmcnt(0)
	v_mfma_f32_32x32x16_bf16 v[32:47], v[134:137], v[138:141], v[32:47]
	v_mfma_f32_32x32x16_bf16 v[16:31], v[134:137], v[150:153], v[16:31]
	v_mfma_f32_32x32x16_bf16 v[114:129], v[134:137], v[160:163], v[114:129]
	v_mfma_f32_32x32x16_bf16 v[0:15], v[134:137], v[164:167], v[0:15]
	s_nop 7
	s_nop 7
	v_mov_b32_e32 v130, v0
	v_mov_b32_e32 v131, v1
	v_mov_b32_e32 v132, v2
	v_mov_b32_e32 v133, v3
	v_mov_b32_e32 v134, v4
	v_mov_b32_e32 v135, v5
	v_mov_b32_e32 v136, v6
	v_mov_b32_e32 v137, v7
	v_mov_b32_e32 v138, v8
	v_mov_b32_e32 v139, v9
	v_mov_b32_e32 v140, v10
	v_mov_b32_e32 v141, v11
	v_mov_b32_e32 v142, v12
	v_mov_b32_e32 v143, v13
	v_mov_b32_e32 v150, v14
	v_mov_b32_e32 v151, v15
	s_mov_b32 s32, 0
	s_mov_b32 s14, s30
	s_mov_b32 s15, s31
	s_waitcnt lgkmcnt(0)
	s_barrier
	s_branch .Lg4a_epi

.Lg2b_cont:
	s_lshl3_add_u32 s30, s5, s33
	s_lshl_b32 s31, s6, 1
	s_mul_i32 s2, s30, 0x150000
	s_add_u32 s22, s46, s2
	s_addc_u32 s23, s47, 0
	s_mul_i32 s2, s31, 0x60000
	s_add_u32 s2, s2, 0xa80000
	s_add_u32 s24, s48, s2
	s_addc_u32 s25, s49, 0
	s_add_u32 s26, s24, 0x60000
	s_addc_u32 s27, s25, 0
	s_waitcnt vmcnt(0) lgkmcnt(0)
	s_barrier
	s_add_u32 m0, s28, 0x0
	s_nop 0
	global_load_lds_dwordx4 v166, s[22:23]
	s_add_u32 m0, s28, 0x400
	s_nop 0
	global_load_lds_dwordx4 v167, s[22:23]
	s_add_u32 s22, s22, 64
	s_addc_u32 s23, s23, 0
	s_add_u32 m0, s28, 0x2000
	s_nop 0
	global_load_lds_dwordx4 v165, s[24:25]
	global_load_lds_dwordx4 v165, s[24:25] offset:1024
	s_add_u32 s24, s24, 0x2000
	s_addc_u32 s25, s25, 0
	s_add_u32 m0, s28, 0x4000
	s_nop 0
	global_load_lds_dwordx4 v165, s[26:27]
	global_load_lds_dwordx4 v165, s[26:27] offset:1024
	s_add_u32 s26, s26, 0x2000
	s_addc_u32 s27, s27, 0
	s_waitcnt vmcnt(0)
	s_barrier
	s_add_u32 m0, s28, 0x6000
	s_nop 0
	global_load_lds_dwordx4 v166, s[22:23]
	s_add_u32 m0, s28, 0x6400
	s_nop 0
	global_load_lds_dwordx4 v167, s[22:23]
	s_add_u32 s22, s22, 64
	s_addc_u32 s23, s23, 0
	s_add_u32 m0, s28, 0x8000
	s_nop 0
	global_load_lds_dwordx4 v165, s[24:25]
	global_load_lds_dwordx4 v165, s[24:25] offset:1024
	s_add_u32 s24, s24, 0x2000
	s_addc_u32 s25, s25, 0
	s_add_u32 m0, s28, 0xa400
	s_nop 0
	global_load_lds_dwordx4 v165, s[26:27]
	global_load_lds_dwordx4 v165, s[26:27] offset:1024
	s_add_u32 s26, s26, 0x2000
	s_addc_u32 s27, s27, 0
	ds_read_b128 v[64:67], v151 offset:0
	ds_read_b128 v[72:75], v157 offset:8192
	ds_read_b128 v[126:129], v157 offset:10240
	ds_read_b128 v[152:155], v157 offset:16384
	ds_read_b128 v[160:163], v157 offset:18432
	ds_read_b128 v[68:71], v151 offset:2048
	s_waitcnt lgkmcnt(4)
	v_mfma_f32_32x32x16_bf16 v[48:63], v[64:67], v[72:75], 0
	s_waitcnt lgkmcnt(3)
	v_mfma_f32_32x32x16_bf16 v[32:47], v[64:67], v[126:129], 0
	s_waitcnt lgkmcnt(2)
	v_mfma_f32_32x32x16_bf16 v[78:93], v[64:67], v[152:155], 0
	s_waitcnt lgkmcnt(1)
	v_mfma_f32_32x32x16_bf16 v[94:109], v[64:67], v[160:163], 0
	ds_read_b128 v[64:67], v156 offset:0
	s_waitcnt lgkmcnt(1)
	v_mfma_f32_32x32x16_bf16 v[132:147], v[68:71], v[160:163], 0
	ds_read_b128 v[160:163], v164 offset:18432
	v_mfma_f32_32x32x16_bf16 v[110:125], v[68:71], v[152:155], 0
	ds_read_b128 v[152:155], v164 offset:16384
	v_mfma_f32_32x32x16_bf16 v[0:15], v[68:71], v[126:129], 0
	ds_read_b128 v[126:129], v164 offset:10240
	v_mfma_f32_32x32x16_bf16 v[16:31], v[68:71], v[72:75], 0
	ds_read_b128 v[72:75], v164 offset:8192
	ds_read_b128 v[68:71], v156 offset:2048
	s_waitcnt lgkmcnt(4)
	v_mfma_f32_32x32x16_bf16 v[94:109], v[64:67], v[160:163], v[94:109]
	s_waitcnt lgkmcnt(3)
	v_mfma_f32_32x32x16_bf16 v[78:93], v[64:67], v[152:155], v[78:93]
	s_waitcnt lgkmcnt(2)
	v_mfma_f32_32x32x16_bf16 v[32:47], v[64:67], v[126:129], v[32:47]
	s_waitcnt lgkmcnt(1)
	v_mfma_f32_32x32x16_bf16 v[48:63], v[64:67], v[72:75], v[48:63]
	s_setprio 2
	s_waitcnt vmcnt(0) lgkmcnt(0)
	s_barrier
	ds_read_b128 v[64:67], v151 offset:24576
	s_add_u32 m0, s28, 0x0
	s_nop 0
	global_load_lds_dwordx4 v166, s[22:23]
	s_add_u32 m0, s28, 0x400
	s_nop 0
	global_load_lds_dwordx4 v167, s[22:23]
	s_add_u32 s22, s22, 64
	s_addc_u32 s23, s23, 0
	v_mfma_f32_32x32x16_bf16 v[16:31], v[68:71], v[72:75], v[16:31]
	ds_read_b128 v[72:75], v157 offset:32768
	s_add_u32 m0, s28, 0x2000
	s_nop 0
	global_load_lds_dwordx4 v165, s[24:25]
	global_load_lds_dwordx4 v165, s[24:25] offset:1024
	s_add_u32 s24, s24, 0x2000
	s_addc_u32 s25, s25, 0
	v_mfma_f32_32x32x16_bf16 v[0:15], v[68:71], v[126:129], v[0:15]
	ds_read_b128 v[126:129], v157 offset:34816
	s_add_u32 m0, s28, 0x4000
	s_nop 0
	global_load_lds_dwordx4 v165, s[26:27]
	global_load_lds_dwordx4 v165, s[26:27] offset:1024
	s_add_u32 s26, s26, 0x2000
	s_addc_u32 s27, s27, 0
	s_setprio 0
	v_mfma_f32_32x32x16_bf16 v[110:125], v[68:71], v[152:155], v[110:125]
	ds_read_b128 v[152:155], v157 offset:41984
	v_mfma_f32_32x32x16_bf16 v[132:147], v[68:71], v[160:163], v[132:147]
	ds_read_b128 v[160:163], v157 offset:44032
	ds_read_b128 v[68:71], v151 offset:26624
	s_waitcnt lgkmcnt(4)
	v_mfma_f32_32x32x16_bf16 v[48:63], v[64:67], v[72:75], v[48:63]
	s_waitcnt lgkmcnt(3)
	v_mfma_f32_32x32x16_bf16 v[32:47], v[64:67], v[126:129], v[32:47]
	s_waitcnt lgkmcnt(2)
	v_mfma_f32_32x32x16_bf16 v[78:93], v[64:67], v[152:155], v[78:93]
	s_waitcnt lgkmcnt(1)
	v_mfma_f32_32x32x16_bf16 v[94:109], v[64:67], v[160:163], v[94:109]
	ds_read_b128 v[64:67], v156 offset:24576
	s_waitcnt lgkmcnt(1)
	v_mfma_f32_32x32x16_bf16 v[132:147], v[68:71], v[160:163], v[132:147]
	ds_read_b128 v[160:163], v164 offset:44032
	v_mfma_f32_32x32x16_bf16 v[110:125], v[68:71], v[152:155], v[110:125]
	ds_read_b128 v[152:155], v164 offset:41984
	v_mfma_f32_32x32x16_bf16 v[0:15], v[68:71], v[126:129], v[0:15]
	ds_read_b128 v[126:129], v164 offset:34816
	v_mfma_f32_32x32x16_bf16 v[16:31], v[68:71], v[72:75], v[16:31]
	ds_read_b128 v[72:75], v164 offset:32768
	ds_read_b128 v[68:71], v156 offset:26624
	s_waitcnt lgkmcnt(4)
	v_mfma_f32_32x32x16_bf16 v[94:109], v[64:67], v[160:163], v[94:109]
	s_waitcnt lgkmcnt(3)
	v_mfma_f32_32x32x16_bf16 v[78:93], v[64:67], v[152:155], v[78:93]
	s_waitcnt lgkmcnt(2)
	v_mfma_f32_32x32x16_bf16 v[32:47], v[64:67], v[126:129], v[32:47]
	s_waitcnt lgkmcnt(1)
	v_mfma_f32_32x32x16_bf16 v[48:63], v[64:67], v[72:75], v[48:63]
	s_setprio 2
	s_waitcnt vmcnt(0) lgkmcnt(0)
	s_barrier
	ds_read_b128 v[64:67], v151 offset:0
	s_add_u32 m0, s28, 0x6000
	s_nop 0
	global_load_lds_dwordx4 v166, s[22:23]
	s_add_u32 m0, s28, 0x6400
	s_nop 0
	global_load_lds_dwordx4 v167, s[22:23]
	s_add_u32 s22, s22, 64
	s_addc_u32 s23, s23, 0
	v_mfma_f32_32x32x16_bf16 v[16:31], v[68:71], v[72:75], v[16:31]
	ds_read_b128 v[72:75], v157 offset:8192
	s_add_u32 m0, s28, 0x8000
	s_nop 0
	global_load_lds_dwordx4 v165, s[24:25]
	global_load_lds_dwordx4 v165, s[24:25] offset:1024
	s_add_u32 s24, s24, 0x2000
	s_addc_u32 s25, s25, 0
	v_mfma_f32_32x32x16_bf16 v[0:15], v[68:71], v[126:129], v[0:15]
	ds_read_b128 v[126:129], v157 offset:10240
	s_add_u32 m0, s28, 0xa400
	s_nop 0
	global_load_lds_dwordx4 v165, s[26:27]
	global_load_lds_dwordx4 v165, s[26:27] offset:1024
	s_add_u32 s26, s26, 0x2000
	s_addc_u32 s27, s27, 0
	s_setprio 0
	v_mfma_f32_32x32x16_bf16 v[110:125], v[68:71], v[152:155], v[110:125]
	ds_read_b128 v[152:155], v157 offset:16384
	v_mfma_f32_32x32x16_bf16 v[132:147], v[68:71], v[160:163], v[132:147]
	ds_read_b128 v[160:163], v157 offset:18432
	ds_read_b128 v[68:71], v151 offset:2048
	s_mov_b32 s29, 22
.Lg2b_kloop:
	s_waitcnt lgkmcnt(4)
	v_mfma_f32_32x32x16_bf16 v[48:63], v[64:67], v[72:75], v[48:63]
	s_waitcnt lgkmcnt(3)
	v_mfma_f32_32x32x16_bf16 v[32:47], v[64:67], v[126:129], v[32:47]
	s_waitcnt lgkmcnt(2)
	v_mfma_f32_32x32x16_bf16 v[78:93], v[64:67], v[152:155], v[78:93]
	s_waitcnt lgkmcnt(1)
	v_mfma_f32_32x32x16_bf16 v[94:109], v[64:67], v[160:163], v[94:109]
	ds_read_b128 v[64:67], v156 offset:0
	s_waitcnt lgkmcnt(1)
	v_mfma_f32_32x32x16_bf16 v[132:147], v[68:71], v[160:163], v[132:147]
	ds_read_b128 v[160:163], v164 offset:18432
	v_mfma_f32_32x32x16_bf16 v[110:125], v[68:71], v[152:155], v[110:125]
	ds_read_b128 v[152:155], v164 offset:16384
	v_mfma_f32_32x32x16_bf16 v[0:15], v[68:71], v[126:129], v[0:15]
	ds_read_b128 v[126:129], v164 offset:10240
	v_mfma_f32_32x32x16_bf16 v[16:31], v[68:71], v[72:75], v[16:31]
	ds_read_b128 v[72:75], v164 offset:8192
	ds_read_b128 v[68:71], v156 offset:2048
	s_waitcnt lgkmcnt(4)
	v_mfma_f32_32x32x16_bf16 v[94:109], v[64:67], v[160:163], v[94:109]
	s_waitcnt lgkmcnt(3)
	v_mfma_f32_32x32x16_bf16 v[78:93], v[64:67], v[152:155], v[78:93]
	s_waitcnt lgkmcnt(2)
	v_mfma_f32_32x32x16_bf16 v[32:47], v[64:67], v[126:129], v[32:47]
	s_waitcnt lgkmcnt(1)
	v_mfma_f32_32x32x16_bf16 v[48:63], v[64:67], v[72:75], v[48:63]
	s_setprio 2
	s_waitcnt vmcnt(0) lgkmcnt(0)
	s_barrier
	ds_read_b128 v[64:67], v151 offset:24576
	s_add_u32 m0, s28, 0x0
	s_nop 0
	global_load_lds_dwordx4 v166, s[22:23]
	s_add_u32 m0, s28, 0x400
	s_nop 0
	global_load_lds_dwordx4 v167, s[22:23]
	s_add_u32 s22, s22, 64
	s_addc_u32 s23, s23, 0
	v_mfma_f32_32x32x16_bf16 v[16:31], v[68:71], v[72:75], v[16:31]
	ds_read_b128 v[72:75], v157 offset:32768
	s_add_u32 m0, s28, 0x2000
	s_nop 0
	global_load_lds_dwordx4 v165, s[24:25]
	global_load_lds_dwordx4 v165, s[24:25] offset:1024
	s_add_u32 s24, s24, 0x2000
	s_addc_u32 s25, s25, 0
	v_mfma_f32_32x32x16_bf16 v[0:15], v[68:71], v[126:129], v[0:15]
	ds_read_b128 v[126:129], v157 offset:34816
	s_add_u32 m0, s28, 0x4000
	s_nop 0
	global_load_lds_dwordx4 v165, s[26:27]
	global_load_lds_dwordx4 v165, s[26:27] offset:1024
	s_add_u32 s26, s26, 0x2000
	s_addc_u32 s27, s27, 0
	s_setprio 0
	v_mfma_f32_32x32x16_bf16 v[110:125], v[68:71], v[152:155], v[110:125]
	ds_read_b128 v[152:155], v157 offset:41984
	v_mfma_f32_32x32x16_bf16 v[132:147], v[68:71], v[160:163], v[132:147]
	ds_read_b128 v[160:163], v157 offset:44032
	ds_read_b128 v[68:71], v151 offset:26624
	s_waitcnt lgkmcnt(4)
	v_mfma_f32_32x32x16_bf16 v[48:63], v[64:67], v[72:75], v[48:63]
	s_waitcnt lgkmcnt(3)
	v_mfma_f32_32x32x16_bf16 v[32:47], v[64:67], v[126:129], v[32:47]
	s_waitcnt lgkmcnt(2)
	v_mfma_f32_32x32x16_bf16 v[78:93], v[64:67], v[152:155], v[78:93]
	s_waitcnt lgkmcnt(1)
	v_mfma_f32_32x32x16_bf16 v[94:109], v[64:67], v[160:163], v[94:109]
	ds_read_b128 v[64:67], v156 offset:24576
	s_waitcnt lgkmcnt(1)
	v_mfma_f32_32x32x16_bf16 v[132:147], v[68:71], v[160:163], v[132:147]
	ds_read_b128 v[160:163], v164 offset:44032
	v_mfma_f32_32x32x16_bf16 v[110:125], v[68:71], v[152:155], v[110:125]
	ds_read_b128 v[152:155], v164 offset:41984
	v_mfma_f32_32x32x16_bf16 v[0:15], v[68:71], v[126:129], v[0:15]
	ds_read_b128 v[126:129], v164 offset:34816
	v_mfma_f32_32x32x16_bf16 v[16:31], v[68:71], v[72:75], v[16:31]
	ds_read_b128 v[72:75], v164 offset:32768
	ds_read_b128 v[68:71], v156 offset:26624
	s_waitcnt lgkmcnt(4)
	v_mfma_f32_32x32x16_bf16 v[94:109], v[64:67], v[160:163], v[94:109]
	s_waitcnt lgkmcnt(3)
	v_mfma_f32_32x32x16_bf16 v[78:93], v[64:67], v[152:155], v[78:93]
	s_waitcnt lgkmcnt(2)
	v_mfma_f32_32x32x16_bf16 v[32:47], v[64:67], v[126:129], v[32:47]
	s_waitcnt lgkmcnt(1)
	v_mfma_f32_32x32x16_bf16 v[48:63], v[64:67], v[72:75], v[48:63]
	s_setprio 2
	s_waitcnt vmcnt(0) lgkmcnt(0)
	s_barrier
	ds_read_b128 v[64:67], v151 offset:0
	s_add_u32 m0, s28, 0x6000
	s_nop 0
	global_load_lds_dwordx4 v166, s[22:23]
	s_add_u32 m0, s28, 0x6400
	s_nop 0
	global_load_lds_dwordx4 v167, s[22:23]
	s_add_u32 s22, s22, 64
	s_addc_u32 s23, s23, 0
	v_mfma_f32_32x32x16_bf16 v[16:31], v[68:71], v[72:75], v[16:31]
	ds_read_b128 v[72:75], v157 offset:8192
	s_add_u32 m0, s28, 0x8000
	s_nop 0
	global_load_lds_dwordx4 v165, s[24:25]
	global_load_lds_dwordx4 v165, s[24:25] offset:1024
	s_add_u32 s24, s24, 0x2000
	s_addc_u32 s25, s25, 0
	v_mfma_f32_32x32x16_bf16 v[0:15], v[68:71], v[126:129], v[0:15]
	ds_read_b128 v[126:129], v157 offset:10240
	s_add_u32 m0, s28, 0xa400
	s_nop 0
	global_load_lds_dwordx4 v165, s[26:27]
	global_load_lds_dwordx4 v165, s[26:27] offset:1024
	s_add_u32 s26, s26, 0x2000
	s_addc_u32 s27, s27, 0
	s_setprio 0
	v_mfma_f32_32x32x16_bf16 v[110:125], v[68:71], v[152:155], v[110:125]
	ds_read_b128 v[152:155], v157 offset:16384
	v_mfma_f32_32x32x16_bf16 v[132:147], v[68:71], v[160:163], v[132:147]
	ds_read_b128 v[160:163], v157 offset:18432
	ds_read_b128 v[68:71], v151 offset:2048
	s_sub_u32 s29, s29, 1
	s_cmp_lg_u32 s29, 0
	s_cbranch_scc1 .Lg2b_kloop
	s_waitcnt lgkmcnt(4)
	v_mfma_f32_32x32x16_bf16 v[48:63], v[64:67], v[72:75], v[48:63]
	s_waitcnt lgkmcnt(3)
	v_mfma_f32_32x32x16_bf16 v[32:47], v[64:67], v[126:129], v[32:47]
	s_waitcnt lgkmcnt(2)
	v_mfma_f32_32x32x16_bf16 v[78:93], v[64:67], v[152:155], v[78:93]
	s_waitcnt lgkmcnt(1)
	v_mfma_f32_32x32x16_bf16 v[94:109], v[64:67], v[160:163], v[94:109]
	ds_read_b128 v[64:67], v156 offset:0
	s_waitcnt lgkmcnt(1)
	v_mfma_f32_32x32x16_bf16 v[132:147], v[68:71], v[160:163], v[132:147]
	ds_read_b128 v[160:163], v164 offset:18432
	v_mfma_f32_32x32x16_bf16 v[110:125], v[68:71], v[152:155], v[110:125]
	ds_read_b128 v[152:155], v164 offset:16384
	v_mfma_f32_32x32x16_bf16 v[0:15], v[68:71], v[126:129], v[0:15]
	ds_read_b128 v[126:129], v164 offset:10240
	v_mfma_f32_32x32x16_bf16 v[16:31], v[68:71], v[72:75], v[16:31]
	ds_read_b128 v[72:75], v164 offset:8192
	ds_read_b128 v[68:71], v156 offset:2048
	s_waitcnt lgkmcnt(4)
	v_mfma_f32_32x32x16_bf16 v[94:109], v[64:67], v[160:163], v[94:109]
	s_waitcnt lgkmcnt(3)
	v_mfma_f32_32x32x16_bf16 v[78:93], v[64:67], v[152:155], v[78:93]
	s_waitcnt lgkmcnt(2)
	v_mfma_f32_32x32x16_bf16 v[32:47], v[64:67], v[126:129], v[32:47]
	s_waitcnt lgkmcnt(1)
	v_mfma_f32_32x32x16_bf16 v[48:63], v[64:67], v[72:75], v[48:63]
	s_waitcnt vmcnt(0) lgkmcnt(0)
	s_barrier
	ds_read_b128 v[64:67], v151 offset:24576
	v_mfma_f32_32x32x16_bf16 v[16:31], v[68:71], v[72:75], v[16:31]
	ds_read_b128 v[72:75], v157 offset:32768
	v_mfma_f32_32x32x16_bf16 v[0:15], v[68:71], v[126:129], v[0:15]
	ds_read_b128 v[126:129], v157 offset:34816
	v_mfma_f32_32x32x16_bf16 v[110:125], v[68:71], v[152:155], v[110:125]
	ds_read_b128 v[152:155], v157 offset:41984
	v_mfma_f32_32x32x16_bf16 v[132:147], v[68:71], v[160:163], v[132:147]
	ds_read_b128 v[160:163], v157 offset:44032
	ds_read_b128 v[68:71], v151 offset:26624
	s_waitcnt lgkmcnt(4)
	v_mfma_f32_32x32x16_bf16 v[48:63], v[64:67], v[72:75], v[48:63]
	s_waitcnt lgkmcnt(3)
	v_mfma_f32_32x32x16_bf16 v[32:47], v[64:67], v[126:129], v[32:47]
	s_waitcnt lgkmcnt(2)
	v_mfma_f32_32x32x16_bf16 v[78:93], v[64:67], v[152:155], v[78:93]
	s_waitcnt lgkmcnt(1)
	v_mfma_f32_32x32x16_bf16 v[94:109], v[64:67], v[160:163], v[94:109]
	ds_read_b128 v[64:67], v156 offset:24576
	s_waitcnt lgkmcnt(1)
	v_mfma_f32_32x32x16_bf16 v[132:147], v[68:71], v[160:163], v[132:147]
	ds_read_b128 v[160:163], v164 offset:44032
	v_mfma_f32_32x32x16_bf16 v[110:125], v[68:71], v[152:155], v[110:125]
	ds_read_b128 v[152:155], v164 offset:41984
	v_mfma_f32_32x32x16_bf16 v[0:15], v[68:71], v[126:129], v[0:15]
	ds_read_b128 v[126:129], v164 offset:34816
	v_mfma_f32_32x32x16_bf16 v[16:31], v[68:71], v[72:75], v[16:31]
	ds_read_b128 v[72:75], v164 offset:32768
	ds_read_b128 v[68:71], v156 offset:26624
	s_waitcnt lgkmcnt(4)
	v_mfma_f32_32x32x16_bf16 v[94:109], v[64:67], v[160:163], v[94:109]
	s_waitcnt lgkmcnt(3)
	v_mfma_f32_32x32x16_bf16 v[78:93], v[64:67], v[152:155], v[78:93]
	s_waitcnt lgkmcnt(2)
	v_mfma_f32_32x32x16_bf16 v[32:47], v[64:67], v[126:129], v[32:47]
	s_waitcnt lgkmcnt(1)
	v_mfma_f32_32x32x16_bf16 v[48:63], v[64:67], v[72:75], v[48:63]
	s_waitcnt lgkmcnt(0)
	v_mfma_f32_32x32x16_bf16 v[16:31], v[68:71], v[72:75], v[16:31]
	v_mfma_f32_32x32x16_bf16 v[0:15], v[68:71], v[126:129], v[0:15]
	v_mfma_f32_32x32x16_bf16 v[110:125], v[68:71], v[152:155], v[110:125]
	v_mfma_f32_32x32x16_bf16 v[132:147], v[68:71], v[160:163], v[132:147]
	s_nop 7
	s_nop 7
	s_mov_b32 s32, 0
	s_lshl_b32 s19, s30, 7
	s_mov_b32 s20, s31

.Lg3b_cont:
	s_lshl3_add_u32 s26, s6, s29
	s_lshl_b32 s27, s7, 1
	s_mul_i32 s1, s26, 0x40000
	s_add_u32 s18, s44, s1
	s_addc_u32 s19, s45, 0
	s_mul_i32 s1, s27, 0x40000
	s_add_u32 s1, s1, 0xd80000
	s_add_u32 s20, s48, s1
	s_addc_u32 s21, s49, 0
	s_add_u32 s22, s20, 0x40000
	s_addc_u32 s23, s21, 0
	s_lshl_b32 s1, s26, 9
	s_add_u32 s34, s2, s1
	s_addc_u32 s35, s3, 0
	s_waitcnt vmcnt(0) lgkmcnt(0)
	s_barrier
	v_and_b32_e32 v167, 63, v148
	v_lshlrev_b32_e32 v167, 4, v167
	s_mov_b32 m0, 0xc400
	s_mov_b64 exec, 0xffffffff
	global_load_lds_dwordx4 v167, s[34:35]
	s_mov_b64 exec, -1
	s_add_u32 m0, s24, 0x0
	s_nop 0
	global_load_lds_dwordx4 v164, s[18:19]
	global_load_lds_dwordx4 v164, s[18:19] offset:1024
	s_add_u32 s18, s18, 0x2000
	s_addc_u32 s19, s19, 0
	s_add_u32 m0, s24, 0x2000
	s_nop 0
	global_load_lds_dwordx4 v164, s[20:21]
	global_load_lds_dwordx4 v164, s[20:21] offset:1024
	s_add_u32 s20, s20, 0x2000
	s_addc_u32 s21, s21, 0
	s_add_u32 m0, s24, 0x4000
	s_nop 0
	global_load_lds_dwordx4 v164, s[22:23]
	global_load_lds_dwordx4 v164, s[22:23] offset:1024
	s_add_u32 s22, s22, 0x2000
	s_addc_u32 s23, s23, 0
	s_waitcnt vmcnt(0)
	s_barrier
	s_add_u32 m0, s24, 0x6000
	s_nop 0
	global_load_lds_dwordx4 v164, s[18:19]
	global_load_lds_dwordx4 v164, s[18:19] offset:1024
	s_add_u32 s18, s18, 0x2000
	s_addc_u32 s19, s19, 0
	s_add_u32 m0, s24, 0x8000
	s_nop 0
	global_load_lds_dwordx4 v164, s[20:21]
	global_load_lds_dwordx4 v164, s[20:21] offset:1024
	s_add_u32 s20, s20, 0x2000
	s_addc_u32 s21, s21, 0
	s_add_u32 m0, s24, 0xa400
	s_nop 0
	global_load_lds_dwordx4 v164, s[22:23]
	global_load_lds_dwordx4 v164, s[22:23] offset:1024
	s_add_u32 s22, s22, 0x2000
	s_addc_u32 s23, s23, 0
	ds_read_b128 v[64:67], v160 offset:0
	ds_read_b128 v[90:93], v162 offset:8192
	ds_read_b128 v[142:145], v162 offset:10240
	ds_read_b128 v[150:153], v162 offset:16384
	ds_read_b128 v[154:157], v162 offset:18432
	ds_read_b128 v[68:71], v160 offset:2048
	s_waitcnt lgkmcnt(4)
	v_mfma_f32_32x32x16_bf16 v[48:63], v[64:67], v[90:93], 0
	s_waitcnt lgkmcnt(3)
	v_mfma_f32_32x32x16_bf16 v[32:47], v[64:67], v[142:145], 0
	s_waitcnt lgkmcnt(2)
	v_mfma_f32_32x32x16_bf16 v[94:109], v[64:67], v[150:153], 0
	s_waitcnt lgkmcnt(1)
	v_mfma_f32_32x32x16_bf16 v[110:125], v[64:67], v[154:157], 0
	ds_read_b128 v[64:67], v161 offset:0
	s_waitcnt lgkmcnt(1)
	v_mfma_f32_32x32x16_bf16 v[74:89], v[68:71], v[154:157], 0
	ds_read_b128 v[154:157], v163 offset:18432
	v_mfma_f32_32x32x16_bf16 v[126:141], v[68:71], v[150:153], 0
	ds_read_b128 v[150:153], v163 offset:16384
	v_mfma_f32_32x32x16_bf16 v[0:15], v[68:71], v[142:145], 0
	ds_read_b128 v[142:145], v163 offset:10240
	v_mfma_f32_32x32x16_bf16 v[16:31], v[68:71], v[90:93], 0
	ds_read_b128 v[90:93], v163 offset:8192
	ds_read_b128 v[68:71], v161 offset:2048
	s_waitcnt lgkmcnt(4)
	v_mfma_f32_32x32x16_bf16 v[110:125], v[64:67], v[154:157], v[110:125]
	s_waitcnt lgkmcnt(3)
	v_mfma_f32_32x32x16_bf16 v[94:109], v[64:67], v[150:153], v[94:109]
	s_waitcnt lgkmcnt(2)
	v_mfma_f32_32x32x16_bf16 v[32:47], v[64:67], v[142:145], v[32:47]
	s_waitcnt lgkmcnt(1)
	v_mfma_f32_32x32x16_bf16 v[48:63], v[64:67], v[90:93], v[48:63]
	s_setprio 2
	s_waitcnt vmcnt(0) lgkmcnt(0)
	s_barrier
	ds_read_b128 v[64:67], v160 offset:24576
	s_add_u32 m0, s24, 0x0
	s_nop 0
	global_load_lds_dwordx4 v164, s[18:19]
	global_load_lds_dwordx4 v164, s[18:19] offset:1024
	s_add_u32 s18, s18, 0x2000
	s_addc_u32 s19, s19, 0
	v_mfma_f32_32x32x16_bf16 v[16:31], v[68:71], v[90:93], v[16:31]
	ds_read_b128 v[90:93], v162 offset:32768
	s_add_u32 m0, s24, 0x2000
	s_nop 0
	global_load_lds_dwordx4 v164, s[20:21]
	global_load_lds_dwordx4 v164, s[20:21] offset:1024
	s_add_u32 s20, s20, 0x2000
	s_addc_u32 s21, s21, 0
	v_mfma_f32_32x32x16_bf16 v[0:15], v[68:71], v[142:145], v[0:15]
	ds_read_b128 v[142:145], v162 offset:34816
	s_add_u32 m0, s24, 0x4000
	s_nop 0
	global_load_lds_dwordx4 v164, s[22:23]
	global_load_lds_dwordx4 v164, s[22:23] offset:1024
	s_add_u32 s22, s22, 0x2000
	s_addc_u32 s23, s23, 0
	s_setprio 0
	v_mfma_f32_32x32x16_bf16 v[126:141], v[68:71], v[150:153], v[126:141]
	ds_read_b128 v[150:153], v162 offset:41984
	v_mfma_f32_32x32x16_bf16 v[74:89], v[68:71], v[154:157], v[74:89]
	ds_read_b128 v[154:157], v162 offset:44032
	ds_read_b128 v[68:71], v160 offset:26624
	s_waitcnt lgkmcnt(4)
	v_mfma_f32_32x32x16_bf16 v[48:63], v[64:67], v[90:93], v[48:63]
	s_waitcnt lgkmcnt(3)
	v_mfma_f32_32x32x16_bf16 v[32:47], v[64:67], v[142:145], v[32:47]
	s_waitcnt lgkmcnt(2)
	v_mfma_f32_32x32x16_bf16 v[94:109], v[64:67], v[150:153], v[94:109]
	s_waitcnt lgkmcnt(1)
	v_mfma_f32_32x32x16_bf16 v[110:125], v[64:67], v[154:157], v[110:125]
	ds_read_b128 v[64:67], v161 offset:24576
	s_waitcnt lgkmcnt(1)
	v_mfma_f32_32x32x16_bf16 v[74:89], v[68:71], v[154:157], v[74:89]
	ds_read_b128 v[154:157], v163 offset:44032
	v_mfma_f32_32x32x16_bf16 v[126:141], v[68:71], v[150:153], v[126:141]
	ds_read_b128 v[150:153], v163 offset:41984
	v_mfma_f32_32x32x16_bf16 v[0:15], v[68:71], v[142:145], v[0:15]
	ds_read_b128 v[142:145], v163 offset:34816
	v_mfma_f32_32x32x16_bf16 v[16:31], v[68:71], v[90:93], v[16:31]
	ds_read_b128 v[90:93], v163 offset:32768
	ds_read_b128 v[68:71], v161 offset:26624
	s_waitcnt lgkmcnt(4)
	v_mfma_f32_32x32x16_bf16 v[110:125], v[64:67], v[154:157], v[110:125]
	s_waitcnt lgkmcnt(3)
	v_mfma_f32_32x32x16_bf16 v[94:109], v[64:67], v[150:153], v[94:109]
	s_waitcnt lgkmcnt(2)
	v_mfma_f32_32x32x16_bf16 v[32:47], v[64:67], v[142:145], v[32:47]
	s_waitcnt lgkmcnt(1)
	v_mfma_f32_32x32x16_bf16 v[48:63], v[64:67], v[90:93], v[48:63]
	s_setprio 2
	s_waitcnt vmcnt(0) lgkmcnt(0)
	s_barrier
	ds_read_b128 v[64:67], v160 offset:0
	s_add_u32 m0, s24, 0x6000
	s_nop 0
	global_load_lds_dwordx4 v164, s[18:19]
	global_load_lds_dwordx4 v164, s[18:19] offset:1024
	s_add_u32 s18, s18, 0x2000
	s_addc_u32 s19, s19, 0
	v_mfma_f32_32x32x16_bf16 v[16:31], v[68:71], v[90:93], v[16:31]
	ds_read_b128 v[90:93], v162 offset:8192
	s_add_u32 m0, s24, 0x8000
	s_nop 0
	global_load_lds_dwordx4 v164, s[20:21]
	global_load_lds_dwordx4 v164, s[20:21] offset:1024
	s_add_u32 s20, s20, 0x2000
	s_addc_u32 s21, s21, 0
	v_mfma_f32_32x32x16_bf16 v[0:15], v[68:71], v[142:145], v[0:15]
	ds_read_b128 v[142:145], v162 offset:10240
	s_add_u32 m0, s24, 0xa400
	s_nop 0
	global_load_lds_dwordx4 v164, s[22:23]
	global_load_lds_dwordx4 v164, s[22:23] offset:1024
	s_add_u32 s22, s22, 0x2000
	s_addc_u32 s23, s23, 0
	s_setprio 0
	v_mfma_f32_32x32x16_bf16 v[126:141], v[68:71], v[150:153], v[126:141]
	ds_read_b128 v[150:153], v162 offset:16384
	v_mfma_f32_32x32x16_bf16 v[74:89], v[68:71], v[154:157], v[74:89]
	ds_read_b128 v[154:157], v162 offset:18432
	ds_read_b128 v[68:71], v160 offset:2048
	s_mov_b32 s25, 14
.Lg3b_kloop:
	s_waitcnt lgkmcnt(4)
	v_mfma_f32_32x32x16_bf16 v[48:63], v[64:67], v[90:93], v[48:63]
	s_waitcnt lgkmcnt(3)
	v_mfma_f32_32x32x16_bf16 v[32:47], v[64:67], v[142:145], v[32:47]
	s_waitcnt lgkmcnt(2)
	v_mfma_f32_32x32x16_bf16 v[94:109], v[64:67], v[150:153], v[94:109]
	s_waitcnt lgkmcnt(1)
	v_mfma_f32_32x32x16_bf16 v[110:125], v[64:67], v[154:157], v[110:125]
	ds_read_b128 v[64:67], v161 offset:0
	s_waitcnt lgkmcnt(1)
	v_mfma_f32_32x32x16_bf16 v[74:89], v[68:71], v[154:157], v[74:89]
	ds_read_b128 v[154:157], v163 offset:18432
	v_mfma_f32_32x32x16_bf16 v[126:141], v[68:71], v[150:153], v[126:141]
	ds_read_b128 v[150:153], v163 offset:16384
	v_mfma_f32_32x32x16_bf16 v[0:15], v[68:71], v[142:145], v[0:15]
	ds_read_b128 v[142:145], v163 offset:10240
	v_mfma_f32_32x32x16_bf16 v[16:31], v[68:71], v[90:93], v[16:31]
	ds_read_b128 v[90:93], v163 offset:8192
	ds_read_b128 v[68:71], v161 offset:2048
	s_waitcnt lgkmcnt(4)
	v_mfma_f32_32x32x16_bf16 v[110:125], v[64:67], v[154:157], v[110:125]
	s_waitcnt lgkmcnt(3)
	v_mfma_f32_32x32x16_bf16 v[94:109], v[64:67], v[150:153], v[94:109]
	s_waitcnt lgkmcnt(2)
	v_mfma_f32_32x32x16_bf16 v[32:47], v[64:67], v[142:145], v[32:47]
	s_waitcnt lgkmcnt(1)
	v_mfma_f32_32x32x16_bf16 v[48:63], v[64:67], v[90:93], v[48:63]
	s_setprio 2
	s_waitcnt vmcnt(0) lgkmcnt(0)
	s_barrier
	ds_read_b128 v[64:67], v160 offset:24576
	s_add_u32 m0, s24, 0x0
	s_nop 0
	global_load_lds_dwordx4 v164, s[18:19]
	global_load_lds_dwordx4 v164, s[18:19] offset:1024
	s_add_u32 s18, s18, 0x2000
	s_addc_u32 s19, s19, 0
	v_mfma_f32_32x32x16_bf16 v[16:31], v[68:71], v[90:93], v[16:31]
	ds_read_b128 v[90:93], v162 offset:32768
	s_add_u32 m0, s24, 0x2000
	s_nop 0
	global_load_lds_dwordx4 v164, s[20:21]
	global_load_lds_dwordx4 v164, s[20:21] offset:1024
	s_add_u32 s20, s20, 0x2000
	s_addc_u32 s21, s21, 0
	v_mfma_f32_32x32x16_bf16 v[0:15], v[68:71], v[142:145], v[0:15]
	ds_read_b128 v[142:145], v162 offset:34816
	s_add_u32 m0, s24, 0x4000
	s_nop 0
	global_load_lds_dwordx4 v164, s[22:23]
	global_load_lds_dwordx4 v164, s[22:23] offset:1024
	s_add_u32 s22, s22, 0x2000
	s_addc_u32 s23, s23, 0
	s_setprio 0
	v_mfma_f32_32x32x16_bf16 v[126:141], v[68:71], v[150:153], v[126:141]
	ds_read_b128 v[150:153], v162 offset:41984
	v_mfma_f32_32x32x16_bf16 v[74:89], v[68:71], v[154:157], v[74:89]
	ds_read_b128 v[154:157], v162 offset:44032
	ds_read_b128 v[68:71], v160 offset:26624
	s_waitcnt lgkmcnt(4)
	v_mfma_f32_32x32x16_bf16 v[48:63], v[64:67], v[90:93], v[48:63]
	s_waitcnt lgkmcnt(3)
	v_mfma_f32_32x32x16_bf16 v[32:47], v[64:67], v[142:145], v[32:47]
	s_waitcnt lgkmcnt(2)
	v_mfma_f32_32x32x16_bf16 v[94:109], v[64:67], v[150:153], v[94:109]
	s_waitcnt lgkmcnt(1)
	v_mfma_f32_32x32x16_bf16 v[110:125], v[64:67], v[154:157], v[110:125]
	ds_read_b128 v[64:67], v161 offset:24576
	s_waitcnt lgkmcnt(1)
	v_mfma_f32_32x32x16_bf16 v[74:89], v[68:71], v[154:157], v[74:89]
	ds_read_b128 v[154:157], v163 offset:44032
	v_mfma_f32_32x32x16_bf16 v[126:141], v[68:71], v[150:153], v[126:141]
	ds_read_b128 v[150:153], v163 offset:41984
	v_mfma_f32_32x32x16_bf16 v[0:15], v[68:71], v[142:145], v[0:15]
	ds_read_b128 v[142:145], v163 offset:34816
	v_mfma_f32_32x32x16_bf16 v[16:31], v[68:71], v[90:93], v[16:31]
	ds_read_b128 v[90:93], v163 offset:32768
	ds_read_b128 v[68:71], v161 offset:26624
	s_waitcnt lgkmcnt(4)
	v_mfma_f32_32x32x16_bf16 v[110:125], v[64:67], v[154:157], v[110:125]
	s_waitcnt lgkmcnt(3)
	v_mfma_f32_32x32x16_bf16 v[94:109], v[64:67], v[150:153], v[94:109]
	s_waitcnt lgkmcnt(2)
	v_mfma_f32_32x32x16_bf16 v[32:47], v[64:67], v[142:145], v[32:47]
	s_waitcnt lgkmcnt(1)
	v_mfma_f32_32x32x16_bf16 v[48:63], v[64:67], v[90:93], v[48:63]
	s_setprio 2
	s_waitcnt vmcnt(0) lgkmcnt(0)
	s_barrier
	ds_read_b128 v[64:67], v160 offset:0
	s_add_u32 m0, s24, 0x6000
	s_nop 0
	global_load_lds_dwordx4 v164, s[18:19]
	global_load_lds_dwordx4 v164, s[18:19] offset:1024
	s_add_u32 s18, s18, 0x2000
	s_addc_u32 s19, s19, 0
	v_mfma_f32_32x32x16_bf16 v[16:31], v[68:71], v[90:93], v[16:31]
	ds_read_b128 v[90:93], v162 offset:8192
	s_add_u32 m0, s24, 0x8000
	s_nop 0
	global_load_lds_dwordx4 v164, s[20:21]
	global_load_lds_dwordx4 v164, s[20:21] offset:1024
	s_add_u32 s20, s20, 0x2000
	s_addc_u32 s21, s21, 0
	v_mfma_f32_32x32x16_bf16 v[0:15], v[68:71], v[142:145], v[0:15]
	ds_read_b128 v[142:145], v162 offset:10240
	s_add_u32 m0, s24, 0xa400
	s_nop 0
	global_load_lds_dwordx4 v164, s[22:23]
	global_load_lds_dwordx4 v164, s[22:23] offset:1024
	s_add_u32 s22, s22, 0x2000
	s_addc_u32 s23, s23, 0
	s_setprio 0
	v_mfma_f32_32x32x16_bf16 v[126:141], v[68:71], v[150:153], v[126:141]
	ds_read_b128 v[150:153], v162 offset:16384
	v_mfma_f32_32x32x16_bf16 v[74:89], v[68:71], v[154:157], v[74:89]
	ds_read_b128 v[154:157], v162 offset:18432
	ds_read_b128 v[68:71], v160 offset:2048
	s_sub_u32 s25, s25, 1
	s_cmp_lg_u32 s25, 0
	s_cbranch_scc1 .Lg3b_kloop
	s_waitcnt lgkmcnt(4)
	v_mfma_f32_32x32x16_bf16 v[48:63], v[64:67], v[90:93], v[48:63]
	s_waitcnt lgkmcnt(3)
	v_mfma_f32_32x32x16_bf16 v[32:47], v[64:67], v[142:145], v[32:47]
	s_waitcnt lgkmcnt(2)
	v_mfma_f32_32x32x16_bf16 v[94:109], v[64:67], v[150:153], v[94:109]
	s_waitcnt lgkmcnt(1)
	v_mfma_f32_32x32x16_bf16 v[110:125], v[64:67], v[154:157], v[110:125]
	ds_read_b128 v[64:67], v161 offset:0
	s_waitcnt lgkmcnt(1)
	v_mfma_f32_32x32x16_bf16 v[74:89], v[68:71], v[154:157], v[74:89]
	ds_read_b128 v[154:157], v163 offset:18432
	v_mfma_f32_32x32x16_bf16 v[126:141], v[68:71], v[150:153], v[126:141]
	ds_read_b128 v[150:153], v163 offset:16384
	v_mfma_f32_32x32x16_bf16 v[0:15], v[68:71], v[142:145], v[0:15]
	ds_read_b128 v[142:145], v163 offset:10240
	v_mfma_f32_32x32x16_bf16 v[16:31], v[68:71], v[90:93], v[16:31]
	ds_read_b128 v[90:93], v163 offset:8192
	ds_read_b128 v[68:71], v161 offset:2048
	s_waitcnt lgkmcnt(4)
	v_mfma_f32_32x32x16_bf16 v[110:125], v[64:67], v[154:157], v[110:125]
	s_waitcnt lgkmcnt(3)
	v_mfma_f32_32x32x16_bf16 v[94:109], v[64:67], v[150:153], v[94:109]
	s_waitcnt lgkmcnt(2)
	v_mfma_f32_32x32x16_bf16 v[32:47], v[64:67], v[142:145], v[32:47]
	s_waitcnt lgkmcnt(1)
	v_mfma_f32_32x32x16_bf16 v[48:63], v[64:67], v[90:93], v[48:63]
	s_waitcnt vmcnt(0) lgkmcnt(0)
	s_barrier
	ds_read_b128 v[64:67], v160 offset:24576
	v_mfma_f32_32x32x16_bf16 v[16:31], v[68:71], v[90:93], v[16:31]
	ds_read_b128 v[90:93], v162 offset:32768
	v_mfma_f32_32x32x16_bf16 v[0:15], v[68:71], v[142:145], v[0:15]
	ds_read_b128 v[142:145], v162 offset:34816
	v_mfma_f32_32x32x16_bf16 v[126:141], v[68:71], v[150:153], v[126:141]
	ds_read_b128 v[150:153], v162 offset:41984
	v_mfma_f32_32x32x16_bf16 v[74:89], v[68:71], v[154:157], v[74:89]
	ds_read_b128 v[154:157], v162 offset:44032
	ds_read_b128 v[68:71], v160 offset:26624
	s_waitcnt lgkmcnt(4)
	v_mfma_f32_32x32x16_bf16 v[48:63], v[64:67], v[90:93], v[48:63]
	s_waitcnt lgkmcnt(3)
	v_mfma_f32_32x32x16_bf16 v[32:47], v[64:67], v[142:145], v[32:47]
	s_waitcnt lgkmcnt(2)
	v_mfma_f32_32x32x16_bf16 v[94:109], v[64:67], v[150:153], v[94:109]
	s_waitcnt lgkmcnt(1)
	v_mfma_f32_32x32x16_bf16 v[110:125], v[64:67], v[154:157], v[110:125]
	ds_read_b128 v[64:67], v161 offset:24576
	s_waitcnt lgkmcnt(1)
	v_mfma_f32_32x32x16_bf16 v[74:89], v[68:71], v[154:157], v[74:89]
	ds_read_b128 v[154:157], v163 offset:44032
	v_mfma_f32_32x32x16_bf16 v[126:141], v[68:71], v[150:153], v[126:141]
	ds_read_b128 v[150:153], v163 offset:41984
	v_mfma_f32_32x32x16_bf16 v[0:15], v[68:71], v[142:145], v[0:15]
	ds_read_b128 v[142:145], v163 offset:34816
	v_mfma_f32_32x32x16_bf16 v[16:31], v[68:71], v[90:93], v[16:31]
	ds_read_b128 v[90:93], v163 offset:32768
	ds_read_b128 v[68:71], v161 offset:26624
	s_waitcnt lgkmcnt(4)
	v_mfma_f32_32x32x16_bf16 v[110:125], v[64:67], v[154:157], v[110:125]
	s_waitcnt lgkmcnt(3)
	v_mfma_f32_32x32x16_bf16 v[94:109], v[64:67], v[150:153], v[94:109]
	s_waitcnt lgkmcnt(2)
	v_mfma_f32_32x32x16_bf16 v[32:47], v[64:67], v[142:145], v[32:47]
	s_waitcnt lgkmcnt(1)
	v_mfma_f32_32x32x16_bf16 v[48:63], v[64:67], v[90:93], v[48:63]
	s_waitcnt lgkmcnt(0)
	v_mfma_f32_32x32x16_bf16 v[16:31], v[68:71], v[90:93], v[16:31]
	v_mfma_f32_32x32x16_bf16 v[0:15], v[68:71], v[142:145], v[0:15]
	v_mfma_f32_32x32x16_bf16 v[126:141], v[68:71], v[150:153], v[126:141]
	v_mfma_f32_32x32x16_bf16 v[74:89], v[68:71], v[154:157], v[74:89]
	s_nop 7
	s_nop 7
	v_mov_b32_e32 v150, v81
	v_mov_b32_e32 v151, v82
	v_mov_b32_e32 v152, v83
	v_mov_b32_e32 v153, v84
	v_mov_b32_e32 v154, v85
	v_mov_b32_e32 v155, v86
	v_mov_b32_e32 v156, v87
	v_mov_b32_e32 v157, v89
	s_mov_b32 s28, 0
	s_mov_b32 s0, s26
	s_mov_b32 s14, s27

.Lg4b_kloop:
	s_waitcnt lgkmcnt(4)
	v_mfma_f32_32x32x16_bf16 v[64:79], v[130:133], v[138:141], v[64:79]
	s_waitcnt lgkmcnt(3)
	v_mfma_f32_32x32x16_bf16 v[48:63], v[130:133], v[150:153], v[48:63]
	s_waitcnt lgkmcnt(2)
	v_mfma_f32_32x32x16_bf16 v[82:97], v[130:133], v[160:163], v[82:97]
	s_waitcnt lgkmcnt(1)
	v_mfma_f32_32x32x16_bf16 v[98:113], v[130:133], v[164:167], v[98:113]
	ds_read_b128 v[130:133], v145 offset:0
	s_waitcnt lgkmcnt(1)
	v_mfma_f32_32x32x16_bf16 v[0:15], v[134:137], v[164:167], v[0:15]
	ds_read_b128 v[164:167], v147 offset:18432
	v_mfma_f32_32x32x16_bf16 v[114:129], v[134:137], v[160:163], v[114:129]
	ds_read_b128 v[160:163], v147 offset:16384
	v_mfma_f32_32x32x16_bf16 v[16:31], v[134:137], v[150:153], v[16:31]
	ds_read_b128 v[150:153], v147 offset:10240
	v_mfma_f32_32x32x16_bf16 v[32:47], v[134:137], v[138:141], v[32:47]
	ds_read_b128 v[138:141], v147 offset:8192
	ds_read_b128 v[134:137], v145 offset:2048
	s_waitcnt lgkmcnt(4)
	v_mfma_f32_32x32x16_bf16 v[98:113], v[130:133], v[164:167], v[98:113]
	s_waitcnt lgkmcnt(3)
	v_mfma_f32_32x32x16_bf16 v[82:97], v[130:133], v[160:163], v[82:97]
	s_waitcnt lgkmcnt(2)
	v_mfma_f32_32x32x16_bf16 v[48:63], v[130:133], v[150:153], v[48:63]
	s_waitcnt lgkmcnt(1)
	v_mfma_f32_32x32x16_bf16 v[64:79], v[130:133], v[138:141], v[64:79]
	s_setprio 2
	s_waitcnt vmcnt(0) lgkmcnt(0)
	s_barrier
	ds_read_b128 v[130:133], v81 offset:24576
	s_add_u32 m0, s28, 0x0
	s_nop 0
	global_load_lds_dwordx4 v157, s[22:23]
	global_load_lds_dwordx4 v157, s[22:23] offset:1024
	s_add_u32 s22, s22, 0x2000
	s_addc_u32 s23, s23, 0
	v_mfma_f32_32x32x16_bf16 v[32:47], v[134:137], v[138:141], v[32:47]
	ds_read_b128 v[138:141], v146 offset:32768
	s_add_u32 m0, s28, 0x2000
	s_nop 0
	global_load_lds_dwordx4 v157, s[24:25]
	global_load_lds_dwordx4 v157, s[24:25] offset:1024
	s_add_u32 s24, s24, 0x2000
	s_addc_u32 s25, s25, 0
	v_mfma_f32_32x32x16_bf16 v[16:31], v[134:137], v[150:153], v[16:31]
	ds_read_b128 v[150:153], v146 offset:34816
	s_add_u32 m0, s28, 0x4000
	s_nop 0
	global_load_lds_dwordx4 v157, s[26:27]
	global_load_lds_dwordx4 v157, s[26:27] offset:1024
	s_add_u32 s26, s26, 0x2000
	s_addc_u32 s27, s27, 0
	s_setprio 0
	v_mfma_f32_32x32x16_bf16 v[114:129], v[134:137], v[160:163], v[114:129]
	ds_read_b128 v[160:163], v146 offset:41984
	v_mfma_f32_32x32x16_bf16 v[0:15], v[134:137], v[164:167], v[0:15]
	ds_read_b128 v[164:167], v146 offset:44032
	ds_read_b128 v[134:137], v81 offset:26624
	s_waitcnt lgkmcnt(4)
	v_mfma_f32_32x32x16_bf16 v[64:79], v[130:133], v[138:141], v[64:79]
	s_waitcnt lgkmcnt(3)
	v_mfma_f32_32x32x16_bf16 v[48:63], v[130:133], v[150:153], v[48:63]
	s_waitcnt lgkmcnt(2)
	v_mfma_f32_32x32x16_bf16 v[82:97], v[130:133], v[160:163], v[82:97]
	s_waitcnt lgkmcnt(1)
	v_mfma_f32_32x32x16_bf16 v[98:113], v[130:133], v[164:167], v[98:113]
	ds_read_b128 v[130:133], v145 offset:24576
	s_waitcnt lgkmcnt(1)
	v_mfma_f32_32x32x16_bf16 v[0:15], v[134:137], v[164:167], v[0:15]
	ds_read_b128 v[164:167], v147 offset:44032
	v_mfma_f32_32x32x16_bf16 v[114:129], v[134:137], v[160:163], v[114:129]
	ds_read_b128 v[160:163], v147 offset:41984
	v_mfma_f32_32x32x16_bf16 v[16:31], v[134:137], v[150:153], v[16:31]
	ds_read_b128 v[150:153], v147 offset:34816
	v_mfma_f32_32x32x16_bf16 v[32:47], v[134:137], v[138:141], v[32:47]
	ds_read_b128 v[138:141], v147 offset:32768
	ds_read_b128 v[134:137], v145 offset:26624
	s_waitcnt lgkmcnt(4)
	v_mfma_f32_32x32x16_bf16 v[98:113], v[130:133], v[164:167], v[98:113]
	s_waitcnt lgkmcnt(3)
	v_mfma_f32_32x32x16_bf16 v[82:97], v[130:133], v[160:163], v[82:97]
	s_waitcnt lgkmcnt(2)
	v_mfma_f32_32x32x16_bf16 v[48:63], v[130:133], v[150:153], v[48:63]
	s_waitcnt lgkmcnt(1)
	v_mfma_f32_32x32x16_bf16 v[64:79], v[130:133], v[138:141], v[64:79]
	s_setprio 2
	s_waitcnt vmcnt(0) lgkmcnt(0)
	s_barrier
	ds_read_b128 v[130:133], v81 offset:0
	s_add_u32 m0, s28, 0x6000
	s_nop 0
	global_load_lds_dwordx4 v157, s[22:23]
	global_load_lds_dwordx4 v157, s[22:23] offset:1024
	s_add_u32 s22, s22, 0x2000
	s_addc_u32 s23, s23, 0
	v_mfma_f32_32x32x16_bf16 v[32:47], v[134:137], v[138:141], v[32:47]
	ds_read_b128 v[138:141], v146 offset:8192
	s_add_u32 m0, s28, 0x8000
	s_nop 0
	global_load_lds_dwordx4 v157, s[24:25]
	global_load_lds_dwordx4 v157, s[24:25] offset:1024
	s_add_u32 s24, s24, 0x2000
	s_addc_u32 s25, s25, 0
	v_mfma_f32_32x32x16_bf16 v[16:31], v[134:137], v[150:153], v[16:31]
	ds_read_b128 v[150:153], v146 offset:10240
	s_add_u32 m0, s28, 0xa400
	s_nop 0
	global_load_lds_dwordx4 v157, s[26:27]
	global_load_lds_dwordx4 v157, s[26:27] offset:1024
	s_add_u32 s26, s26, 0x2000
	s_addc_u32 s27, s27, 0
	s_setprio 0
	v_mfma_f32_32x32x16_bf16 v[114:129], v[134:137], v[160:163], v[114:129]
	ds_read_b128 v[160:163], v146 offset:16384
	v_mfma_f32_32x32x16_bf16 v[0:15], v[134:137], v[164:167], v[0:15]
	ds_read_b128 v[164:167], v146 offset:18432
	ds_read_b128 v[134:137], v81 offset:2048
	s_sub_u32 s29, s29, 1
	s_cmp_lg_u32 s29, 0
	s_cbranch_scc1 .Lg4b_kloop
	s_waitcnt lgkmcnt(4)
	v_mfma_f32_32x32x16_bf16 v[64:79], v[130:133], v[138:141], v[64:79]
	s_waitcnt lgkmcnt(3)
	v_mfma_f32_32x32x16_bf16 v[48:63], v[130:133], v[150:153], v[48:63]
	s_waitcnt lgkmcnt(2)
	v_mfma_f32_32x32x16_bf16 v[82:97], v[130:133], v[160:163], v[82:97]
	s_waitcnt lgkmcnt(1)
	v_mfma_f32_32x32x16_bf16 v[98:113], v[130:133], v[164:167], v[98:113]
	ds_read_b128 v[130:133], v145 offset:0
	s_waitcnt lgkmcnt(1)
	v_mfma_f32_32x32x16_bf16 v[0:15], v[134:137], v[164:167], v[0:15]
	ds_read_b128 v[164:167], v147 offset:18432
	v_mfma_f32_32x32x16_bf16 v[114:129], v[134:137], v[160:163], v[114:129]
	ds_read_b128 v[160:163], v147 offset:16384
	v_mfma_f32_32x32x16_bf16 v[16:31], v[134:137], v[150:153], v[16:31]
	ds_read_b128 v[150:153], v147 offset:10240
	v_mfma_f32_32x32x16_bf16 v[32:47], v[134:137], v[138:141], v[32:47]
	ds_read_b128 v[138:141], v147 offset:8192
	ds_read_b128 v[134:137], v145 offset:2048
	s_waitcnt lgkmcnt(4)
	v_mfma_f32_32x32x16_bf16 v[98:113], v[130:133], v[164:167], v[98:113]
	s_waitcnt lgkmcnt(3)
	v_mfma_f32_32x32x16_bf16 v[82:97], v[130:133], v[160:163], v[82:97]
	s_waitcnt lgkmcnt(2)
	v_mfma_f32_32x32x16_bf16 v[48:63], v[130:133], v[150:153], v[48:63]
	s_waitcnt lgkmcnt(1)
	v_mfma_f32_32x32x16_bf16 v[64:79], v[130:133], v[138:141], v[64:79]
	s_waitcnt vmcnt(0) lgkmcnt(0)
	s_barrier
	ds_read_b128 v[130:133], v81 offset:24576
	v_mfma_f32_32x32x16_bf16 v[32:47], v[134:137], v[138:141], v[32:47]
	ds_read_b128 v[138:141], v146 offset:32768
	v_mfma_f32_32x32x16_bf16 v[16:31], v[134:137], v[150:153], v[16:31]
	ds_read_b128 v[150:153], v146 offset:34816
	v_mfma_f32_32x32x16_bf16 v[114:129], v[134:137], v[160:163], v[114:129]
	ds_read_b128 v[160:163], v146 offset:41984
	v_mfma_f32_32x32x16_bf16 v[0:15], v[134:137], v[164:167], v[0:15]
	ds_read_b128 v[164:167], v146 offset:44032
	ds_read_b128 v[134:137], v81 offset:26624
	s_waitcnt lgkmcnt(4)
	v_mfma_f32_32x32x16_bf16 v[64:79], v[130:133], v[138:141], v[64:79]
	s_waitcnt lgkmcnt(3)
	v_mfma_f32_32x32x16_bf16 v[48:63], v[130:133], v[150:153], v[48:63]
	s_waitcnt lgkmcnt(2)
	v_mfma_f32_32x32x16_bf16 v[82:97], v[130:133], v[160:163], v[82:97]
	s_waitcnt lgkmcnt(1)
	v_mfma_f32_32x32x16_bf16 v[98:113], v[130:133], v[164:167], v[98:113]
	ds_read_b128 v[130:133], v145 offset:24576
	s_waitcnt lgkmcnt(1)
	v_mfma_f32_32x32x16_bf16 v[0:15], v[134:137], v[164:167], v[0:15]
	ds_read_b128 v[164:167], v147 offset:44032
	v_mfma_f32_32x32x16_bf16 v[114:129], v[134:137], v[160:163], v[114:129]
	ds_read_b128 v[160:163], v147 offset:41984
	v_mfma_f32_32x32x16_bf16 v[16:31], v[134:137], v[150:153], v[16:31]
	ds_read_b128 v[150:153], v147 offset:34816
	v_mfma_f32_32x32x16_bf16 v[32:47], v[134:137], v[138:141], v[32:47]
	ds_read_b128 v[138:141], v147 offset:32768
	ds_read_b128 v[134:137], v145 offset:26624
	s_waitcnt lgkmcnt(4)
	v_mfma_f32_32x32x16_bf16 v[98:113], v[130:133], v[164:167], v[98:113]
	s_waitcnt lgkmcnt(3)
	v_mfma_f32_32x32x16_bf16 v[82:97], v[130:133], v[160:163], v[82:97]
	s_waitcnt lgkmcnt(2)
	v_mfma_f32_32x32x16_bf16 v[48:63], v[130:133], v[150:153], v[48:63]
	s_waitcnt lgkmcnt(1)
	v_mfma_f32_32x32x16_bf16 v[64:79], v[130:133], v[138:141], v[64:79]
	s_waitcnt lgkmcnt(0)
	v_mfma_f32_32x32x16_bf16 v[32:47], v[134:137], v[138:141], v[32:47]
	v_mfma_f32_32x32x16_bf16 v[16:31], v[134:137], v[150:153], v[16:31]
	v_mfma_f32_32x32x16_bf16 v[114:129], v[134:137], v[160:163], v[114:129]
	v_mfma_f32_32x32x16_bf16 v[0:15], v[134:137], v[164:167], v[0:15]
	s_nop 7
	s_nop 7
	v_mov_b32_e32 v130, v0
	v_mov_b32_e32 v131, v1
	v_mov_b32_e32 v132, v2
	v_mov_b32_e32 v133, v3
	v_mov_b32_e32 v134, v4
	v_mov_b32_e32 v135, v5
	v_mov_b32_e32 v136, v6
	v_mov_b32_e32 v137, v7
	v_mov_b32_e32 v138, v8
	v_mov_b32_e32 v139, v9
	v_mov_b32_e32 v140, v10
	v_mov_b32_e32 v141, v11
	v_mov_b32_e32 v142, v12
	v_mov_b32_e32 v143, v13
	v_mov_b32_e32 v150, v14
	v_mov_b32_e32 v151, v15
	s_mov_b32 s32, 0
	s_mov_b32 s16, s30
	s_mov_b32 s17, s31
	s_waitcnt lgkmcnt(0)
	s_barrier
	s_branch .Lg4b_epi
